# hyena Toeplitz MFMA loops software-pipelined (ds_read 2 steps ahead) + LDS stride 5152->5184 for conflict-free afrag reads
# speedup vs baseline: 1.0204x; 1.0204x over previous
.LBB0_234:
	s_or_b64 exec, exec, s[0:1]
	v_readlane_b32 s8, v252, 18
	v_readlane_b32 s12, v252, 22
	v_readlane_b32 s13, v252, 23
	s_add_u32 s74, s12, 0x15c91600
	s_addc_u32 s75, s13, 0
	s_add_u32 s24, s12, 0x3200000
	s_addc_u32 s25, s13, 0
	s_lshl_b32 s5, s54, 5
	v_readlane_b32 s14, v252, 24
	v_readlane_b32 s15, v252, 25
	s_add_u32 s88, s12, 0x3c91600
	s_mul_i32 s0, s15, s14
	s_addc_u32 s89, s13, 0
	s_lshl_b32 s29, s14, 5
	s_mul_i32 s70, s0, s33
	s_add_u32 s0, s12, 0x338e200
	v_readlane_b32 s10, v252, 20
	s_addc_u32 s1, s13, 0
	v_readlane_b32 s11, v252, 21
	s_add_u32 s10, s12, 0x338e400
	s_addc_u32 s11, s13, 0
	s_add_u32 s26, s12, 0x338e500
	s_addc_u32 s27, s13, 0
	s_add_u32 s30, s12, 0x338e600
	s_addc_u32 s31, s13, 0
	s_add_u32 s90, s12, 0x338e700
	s_addc_u32 s91, s13, 0
	s_add_u32 s22, s12, 0x338e800
	s_addc_u32 s23, s13, 0
	s_add_u32 s78, s12, 0x338e900
	v_writelane_b32 v253, s0, 28
	s_addc_u32 s79, s13, 0
	v_readlane_b32 s9, v252, 19
	v_writelane_b32 v253, s1, 29
	s_add_u32 s0, s12, 0x338ea00
	s_addc_u32 s1, s13, 0
	v_writelane_b32 v253, s0, 30
	v_exp_f32_e32 v210, 0xbfd49a78
	v_writelane_b32 v255, s26, 0
	v_writelane_b32 v253, s1, 31
	s_add_u32 s0, s12, 0x338eb00
	s_addc_u32 s1, s13, 0
	v_writelane_b32 v253, s0, 32
	v_writelane_b32 v255, s27, 1
	v_writelane_b32 v255, s30, 2
	v_writelane_b32 v253, s1, 33
	s_add_u32 s0, s12, 0x338ec00
	s_addc_u32 s1, s13, 0
	v_writelane_b32 v253, s0, 34
	v_exp_f32_e32 v235, 0xc0549a78
	s_waitcnt lgkmcnt(0)
	v_mbcnt_lo_u32_b32 v0, -1, 0
	v_writelane_b32 v253, s1, 35
	s_add_u32 s0, s12, 0x338ed00
	s_addc_u32 s1, s13, 0
	v_writelane_b32 v253, s0, 36
	v_writelane_b32 v255, s31, 3
	v_mbcnt_hi_u32_b32 v224, -1, v0
	v_writelane_b32 v253, s1, 37
	s_add_u32 s0, s12, 0x338ee00
	s_addc_u32 s1, s13, 0
	v_writelane_b32 v253, s0, 38
	v_writelane_b32 v255, s29, 4
	v_and_b32_e32 v0, 64, v224
	v_writelane_b32 v253, s1, 39
	s_add_u32 s0, s12, 0x338ef00
	s_addc_u32 s1, s13, 0
	v_writelane_b32 v253, s0, 40
	v_writelane_b32 v255, s88, 5
	v_mov_b32_e32 v1, 0
	v_writelane_b32 v253, s1, 41
	s_add_u32 s0, s12, 0x338f000
	s_addc_u32 s1, s13, 0
	v_writelane_b32 v253, s0, 42
	v_mov_b32_e32 v220, 0x358637bd
	v_mov_b32_e32 v221, 0x1000
	v_writelane_b32 v253, s1, 43
	s_add_u32 s0, s12, 0x338f100
	s_addc_u32 s1, s13, 0
	v_writelane_b32 v253, s0, 44
	v_mov_b32_e32 v229, 0x3ecc95a3
	v_add_u32_e32 v225, 64, v0
	v_writelane_b32 v253, s1, 45
	s_add_u32 s0, s12, 0x338f200
	s_addc_u32 s1, s13, 0
	v_writelane_b32 v253, s0, 46
	v_xor_b32_e32 v228, 32, v224
	v_xor_b32_e32 v227, 16, v224
	v_writelane_b32 v253, s1, 47
	s_add_u32 s0, s12, 0x338f300
	s_addc_u32 s1, s13, 0
	v_writelane_b32 v253, s0, 48
	v_xor_b32_e32 v226, 8, v224
	v_mov_b32_e32 v234, 0x7f800000
	v_writelane_b32 v253, s1, 49
	s_add_u32 s0, s12, 0x3391400
	s_addc_u32 s1, s13, 0
	v_writelane_b32 v253, s0, 50
	s_mov_b32 s71, 0x38e38e39
	s_movk_i32 s73, 0xf700
	v_writelane_b32 v253, s1, 51
	s_add_u32 s0, s12, 0x3391500
	s_addc_u32 s1, s13, 0
	s_add_u32 s80, s12, 0x1ec91600
	v_writelane_b32 v253, s0, 52
	s_addc_u32 s81, s13, 0
	s_mov_b32 s93, 0x800000
	v_writelane_b32 v253, s1, 53
	s_add_u32 s0, s12, 0x36b11600
	s_addc_u32 s1, s13, 0
	v_writelane_b32 v253, s0, 54
	s_movk_i32 s28, 0x2000
	s_mov_b32 s61, 0x11fff
	v_writelane_b32 v253, s1, 55
	s_add_u32 s0, s12, 0x3e711600
	s_addc_u32 s1, s13, 0
	v_writelane_b32 v253, s0, 56
	s_mov_b32 s97, 0x42800000
	s_movk_i32 s95, 0xf40
	v_writelane_b32 v253, s1, 57
	s_add_u32 s0, s12, 0x3e831600
	s_addc_u32 s1, s13, 0
	v_writelane_b32 v253, s0, 58
	s_ashr_i32 s59, s54, 31
	s_ashr_i32 s55, s14, 31
	v_writelane_b32 v253, s1, 59
	s_lshr_b32 s0, s59, 29
	s_add_i32 s0, s54, s0
	s_ashr_i32 s1, s0, 3
	s_and_b32 s0, s0, -8
	s_sub_i32 s6, s54, s0
	s_add_u32 s0, s12, 0x3000000
	v_writelane_b32 v253, s0, 60
	s_addc_u32 s0, s13, 0
	s_cmpk_lt_i32 s54, 0x480
	v_writelane_b32 v253, s0, 61
	s_cselect_b64 s[8:9], -1, 0
	v_writelane_b32 v253, s8, 62
	s_movk_i32 s33, 0x7fff
	s_movk_i32 s60, 0x210
	v_writelane_b32 v253, s9, 63
	s_add_u32 s8, s12, 0x38f11600
	s_addc_u32 s9, s13, 0
	v_writelane_b32 v254, s8, 0
	s_mov_b32 s53, 0x1ed49000
	s_mov_b32 s72, 0x429cc470
	v_writelane_b32 v254, s9, 1
	s_add_u32 s8, s12, 0x2ff11600
	s_addc_u32 s9, s13, 0
	v_writelane_b32 v254, s8, 2
	s_add_u32 s0, s12, 0x338c000
	s_mov_b64 s[62:63], -1
	v_writelane_b32 v254, s9, 3
	v_writelane_b32 v254, s0, 4
	s_addc_u32 s0, s13, 0
	v_writelane_b32 v254, s0, 5
	s_add_u32 s0, s12, 0x3b91600
	v_writelane_b32 v254, s0, 6
	s_addc_u32 s0, s13, 0
	v_writelane_b32 v254, s0, 7
	s_add_u32 s0, s12, 0x3391600
	v_writelane_b32 v254, s0, 8
	s_addc_u32 s0, s13, 0
	v_writelane_b32 v254, s0, 9
	s_add_u32 s0, s12, 0x3d711600
	v_writelane_b32 v254, s0, 10
	s_addc_u32 s0, s13, 0
	s_add_u32 s8, s12, 0x3b311600
	v_writelane_b32 v254, s0, 11
	s_addc_u32 s9, s13, 0
	v_writelane_b32 v254, s8, 12
	s_mov_b64 s[56:57], 0x80
	s_mov_b32 s58, 0x3b800000
	v_writelane_b32 v254, s9, 13
	s_add_u32 s8, s12, 0x32311600
	s_addc_u32 s9, s13, 0
	v_writelane_b32 v254, s8, 14
	s_add_u32 s0, s12, 0xb00000
	s_mov_b32 s92, 0x358637bd
	v_writelane_b32 v254, s9, 15
	v_writelane_b32 v254, s0, 16
	s_addc_u32 s0, s13, 0
	v_writelane_b32 v254, s0, 17
	s_add_u32 s0, s12, 0xf00000
	v_writelane_b32 v254, s0, 18
	s_addc_u32 s0, s13, 0
	v_writelane_b32 v254, s0, 19
	s_add_u32 s0, s12, 0x2500000
	v_writelane_b32 v254, s0, 20
	s_addc_u32 s0, s13, 0
	v_writelane_b32 v254, s0, 21
	s_cmp_lt_i32 s6, 0
	s_movk_i32 s0, 0x91
	s_cselect_b32 s0, s0, 0x90
	s_mul_i32 s0, s6, s0
	s_add_i32 s0, s0, s1
	v_writelane_b32 v254, s1, 22
	s_ashr_i32 s1, s0, 31
	s_lshr_b32 s1, s1, 27
	s_add_i32 s1, s0, s1
	s_and_b32 s3, s1, 0xffe0
	s_sub_i32 s0, s0, s3
	s_bfe_i32 s3, s0, 0x80000
	s_bfe_u32 s3, s3, 0x3000c
	s_add_i32 s3, s0, s3
	s_and_b32 s4, s3, 0xf8
	s_sub_i32 s0, s0, s4
	s_ashr_i32 s1, s1, 5
	s_lshl_b32 s1, s1, 3
	s_sext_i32_i8 s0, s0
	s_add_i32 s4, s1, s0
	s_bfe_i32 s0, s3, 0x80000
	s_sext_i32_i16 s0, s0
	s_ashr_i32 s1, s0, 3
	s_lshr_b32 s0, s0, 3
	v_writelane_b32 v254, s1, 23
	s_bfe_i64 s[0:1], s[0:1], 0x100000
	s_lshl_b64 s[0:1], s[0:1], 18
	v_writelane_b32 v254, s0, 24
	s_mov_b32 s9, 0
	v_writelane_b32 v252, s8, 0
	v_writelane_b32 v254, s1, 25
	v_writelane_b32 v254, s6, 26
	s_lshr_b32 s0, s6, 31
	s_mul_i32 s1, s4, 0xf4000
	v_writelane_b32 v254, s0, 27
	s_mul_hi_i32 s0, s4, 0xf4000
	s_add_u32 s6, s80, s1
	v_writelane_b32 v254, s4, 28
	s_addc_u32 s7, s81, s0
	s_add_u32 s0, s6, 0x7a000
	v_writelane_b32 v254, s6, 29
	s_addc_u32 s1, s7, 0
	v_writelane_b32 v252, s9, 1
	v_writelane_b32 v254, s7, 30
	v_writelane_b32 v254, s0, 31
	v_writelane_b32 v252, s10, 2
	v_writelane_b32 v252, s11, 3
	v_writelane_b32 v254, s1, 32
	v_writelane_b32 v254, s5, 33
	s_or_b32 s0, s5, 3
	v_writelane_b32 v254, s0, 34
	s_add_i32 s0, 0, 0x20000
	v_writelane_b32 v254, s0, 35
	s_add_i32 s0, 0, 0x20004
	v_writelane_b32 v254, s0, 36
	s_add_i32 s0, 0, 0xa200
	v_writelane_b32 v252, s12, 4
	v_writelane_b32 v254, s0, 37
	s_add_i32 s0, 0, 0x3c0
	v_writelane_b32 v252, s13, 5
	v_writelane_b32 v254, s0, 38
	s_add_i32 s0, 0, 0x5c0
	v_writelane_b32 v252, s14, 6
	v_writelane_b32 v254, s0, 39
	s_add_i32 s0, 0, 0x7c0
	v_writelane_b32 v252, s15, 7
	v_writelane_b32 v254, s0, 40
	s_add_i32 s0, 0, 0x9c0
	v_writelane_b32 v252, s16, 8
	v_writelane_b32 v254, s0, 41
	s_add_i32 s0, 0, 0xbc0
	v_writelane_b32 v252, s17, 9
	v_writelane_b32 v254, s0, 42
	s_add_i32 s0, 0, 0xdc0
	v_writelane_b32 v252, s18, 10
	v_writelane_b32 v254, s0, 43
	s_add_i32 s0, 0, 0xfc0
	v_writelane_b32 v252, s19, 11
	v_writelane_b32 v254, s0, 44
	s_add_i32 s0, 0, 0x11c0
	v_writelane_b32 v252, s20, 12
	v_writelane_b32 v254, s0, 45
	v_writelane_b32 v252, s21, 13
	v_writelane_b32 v252, s22, 14
	v_writelane_b32 v254, s70, 46
	v_writelane_b32 v252, s23, 15
	v_writelane_b32 v254, s10, 47
	s_mov_b32 s0, s54
	s_mov_b64 s[4:5], 0
	v_writelane_b32 v254, s11, 48
	v_writelane_b32 v254, s90, 49
	s_mov_b64 s[2:3], 0x40000
	s_mov_b32 s94, 0x3e38aa3b
	v_writelane_b32 v254, s91, 50
	v_writelane_b32 v254, s22, 51
	s_mov_b32 s96, 0x3e16c740
	s_mov_b32 s52, 0
	v_writelane_b32 v254, s23, 52
	v_writelane_b32 v254, s78, 53
	v_writelane_b32 v255, s89, 6
	s_nop 0
	v_writelane_b32 v254, s79, 54
	v_writelane_b32 v254, s80, 55
	s_barrier
	s_nop 0
	v_writelane_b32 v254, s81, 56
	v_writelane_b32 v254, s0, 57
	s_nop 1
	v_writelane_b32 v254, s1, 58
	v_writelane_b32 v254, s74, 59
	s_nop 1
	v_writelane_b32 v254, s75, 60
	v_writelane_b32 v254, s55, 61
	v_writelane_b32 v254, s24, 62
	s_nop 1
	v_writelane_b32 v254, s25, 63
	s_branch .LBB0_237

.LBB0_627:
	s_or_b64 exec, exec, s[18:19]
	s_mov_b32 s4, 0x1000706
	s_waitcnt vmcnt(0)
	v_perm_b32 v10, v5, v6, s4
	v_perm_b32 v11, v6, v7, s4
	v_perm_b32 v12, v7, v8, s4
	v_lshl_add_u32 v17, v16, 4, 0
	v_perm_b32 v13, v8, v9, s4
	v_pk_mov_b32 v[20:21], v[6:7], v[8:9] op_sel:[1,0]
	v_pk_mov_b32 v[18:19], v[4:5], v[6:7] op_sel:[1,0]
	v_perm_b32 v24, v4, v5, s4
	v_mov_b32_e32 v25, v10
	v_mov_b32_e32 v26, v11
	v_mov_b32_e32 v27, v12
	ds_write_b128 v17, v[6:9]
	ds_write_b128 v17, v[10:13] offset:5184
	ds_write_b128 v17, v[18:21] offset:10368
	ds_write_b128 v17, v[24:27] offset:15552
	ds_write_b128 v17, v[4:7] offset:20736
	v_perm_b32 v6, v3, v4, s4
	v_mov_b32_e32 v7, v24
	v_mov_b32_e32 v8, v10
	v_mov_b32_e32 v9, v11
	v_pk_mov_b32 v[12:13], v[2:3], v[4:5] op_sel:[1,0]
	v_mov_b32_e32 v14, v18
	v_mov_b32_e32 v15, v19
	v_perm_b32 v2, v2, v3, s4
	v_mov_b32_e32 v3, v6
	v_mov_b32_e32 v4, v24
	v_mov_b32_e32 v5, v10
	ds_write_b128 v17, v[6:9] offset:25920
	ds_write_b128 v17, v[12:15] offset:31104
	ds_write_b128 v17, v[2:5] offset:36288

.LBB0_636:
	s_or_b64 exec, exec, s[12:13]
	v_and_b32_e32 v18, 7, v16
	v_mul_u32_u24_e32 v30, 0x1440, v18
	s_waitcnt vmcnt(1)
	v_lshlrev_b32_e32 v18, 16, v6
	v_and_b32_e32 v6, 0xffff0000, v6
	v_mov_b32_e32 v64, v63
	v_mov_b32_e32 v28, v6
	v_mov_b32_e32 v29, v18
	v_pk_mul_f32 v[28:29], v[64:65], v[28:29]
	v_lshlrev_b32_e32 v19, 16, v7
	v_fma_f32 v12, v62, v12, v29
	v_pk_mul_f32 v[26:27], v[62:63], v[18:19]
	v_add_f32_e32 v12, v28, v12
	v_and_b32_e32 v7, 0xffff0000, v7
	v_add_f32_e32 v31, v73, v12
	v_fma_f32 v12, v65, v6, v26
	v_add_f32_e32 v12, v27, v12
	v_pk_mul_f32 v[26:27], v[62:63], v[6:7]
	v_mov_b32_e32 v18, v63
	v_fma_f32 v6, v65, v19, v26
	v_add_f32_e32 v6, v27, v6
	v_lshlrev_b32_e32 v26, 16, v8
	v_add_f32_e32 v33, v73, v6
	v_mov_b32_e32 v6, v26
	v_pk_mul_f32 v[28:29], v[64:65], v[6:7]
	v_and_b32_e32 v8, 0xffff0000, v8
	v_fma_f32 v6, v62, v19, v29
	v_add_f32_e32 v6, v28, v6
	v_add_f32_e32 v34, v73, v6
	v_mov_b32_e32 v19, v62
	v_mov_b32_e32 v6, v8
	v_pk_mul_f32 v[6:7], v[18:19], v[6:7]
	v_lshlrev_b32_e32 v27, 16, v9
	v_fma_f32 v7, v65, v26, v7
	v_pk_mul_f32 v[28:29], v[62:63], v[26:27]
	v_add_f32_e32 v6, v6, v7
	v_add_f32_e32 v26, v73, v6
	v_fma_f32 v6, v65, v8, v28
	v_and_b32_e32 v9, 0xffff0000, v9
	v_add_f32_e32 v6, v29, v6
	v_add_f32_e32 v28, v73, v6
	v_pk_mul_f32 v[6:7], v[62:63], v[8:9]
	v_add_f32_e32 v32, v73, v12
	v_fma_f32 v6, v65, v27, v6
	v_add_f32_e32 v6, v7, v6
	v_mov_b32_e32 v12, v27
	v_lshlrev_b32_e32 v24, 4, v16
	v_add_f32_e32 v29, v73, v6
	v_pk_mul_f32 v[6:7], v[62:63], v[12:13]
	v_and_b32_e32 v0, 31, v16
	v_and_b32_e32 v14, 0x1f0, v24
	v_fma_f32 v6, v65, v9, v6
	v_add_u32_e32 v14, 0, v14
	v_mul_u32_u24_e32 v15, 0x210, v0
	v_add_f32_e32 v6, v6, v7
	s_waitcnt lgkmcnt(0)
	s_barrier
	v_add_f32_e32 v9, v73, v6
	v_cvt_pk_bf16_f32 v6, v31, v32
	v_mad_u64_u32 v[12:13], s[0:1], v10, s60, v[14:15]
	v_cvt_pk_bf16_f32 v7, v33, v34
	v_cvt_pk_bf16_f32 v8, v26, v28
	v_cvt_pk_bf16_f32 v9, v29, v9
	ds_write_b128 v12, v[6:9] offset:41472
	s_waitcnt vmcnt(0)
	v_lshlrev_b32_e32 v6, 16, v2
	v_and_b32_e32 v2, 0xffff0000, v2
	v_mov_b32_e32 v12, v2
	v_mov_b32_e32 v13, v6
	v_lshlrev_b32_e32 v7, 16, v3
	v_pk_mul_f32 v[12:13], v[64:65], v[12:13]
	v_pk_mul_f32 v[8:9], v[62:63], v[6:7]
	v_fma_f32 v6, v62, v25, v13
	v_add_f32_e32 v6, v12, v6
	v_and_b32_e32 v3, 0xffff0000, v3
	v_add_f32_e32 v25, v73, v6
	v_fma_f32 v6, v65, v2, v8
	v_add_f32_e32 v6, v9, v6
	v_pk_mul_f32 v[8:9], v[62:63], v[2:3]
	v_add_f32_e32 v26, v73, v6
	v_fma_f32 v2, v65, v7, v8
	v_add_f32_e32 v2, v9, v2
	v_lshlrev_b32_e32 v8, 16, v4
	v_add_f32_e32 v27, v73, v2
	v_mov_b32_e32 v2, v8
	v_pk_mul_f32 v[12:13], v[64:65], v[2:3]
	v_and_b32_e32 v4, 0xffff0000, v4
	v_fma_f32 v2, v62, v7, v13
	v_add_f32_e32 v2, v12, v2
	v_add_f32_e32 v12, v73, v2
	v_mov_b32_e32 v2, v4
	v_pk_mul_f32 v[2:3], v[18:19], v[2:3]
	v_lshlrev_b32_e32 v9, 16, v5
	v_fma_f32 v3, v65, v8, v3
	v_pk_mul_f32 v[6:7], v[62:63], v[8:9]
	v_add_f32_e32 v2, v2, v3
	v_add_f32_e32 v8, v73, v2
	v_fma_f32 v2, v65, v4, v6
	v_and_b32_e32 v5, 0xffff0000, v5
	v_add_f32_e32 v2, v7, v2
	v_add_f32_e32 v6, v73, v2
	v_pk_mul_f32 v[2:3], v[62:63], v[4:5]
	v_mov_b32_e32 v10, v9
	v_fma_f32 v2, v65, v9, v2
	v_add_f32_e32 v2, v3, v2
	v_add_f32_e32 v7, v73, v2
	v_pk_mul_f32 v[2:3], v[62:63], v[10:11]
	v_bfe_u32 v22, v16, 5, 1
	v_fma_f32 v2, v65, v5, v2
	v_add_f32_e32 v2, v2, v3
	v_add_f32_e32 v5, v73, v2
	v_cvt_pk_bf16_f32 v2, v25, v26
	v_cvt_pk_bf16_f32 v3, v27, v12
	v_cvt_pk_bf16_f32 v4, v8, v6
	v_cvt_pk_bf16_f32 v5, v7, v5
	v_mad_u64_u32 v[6:7], s[0:1], v17, s60, v[14:15]
	ds_write_b128 v6, v[2:5] offset:41472
	v_lshlrev_b32_e32 v2, 4, v22
	v_lshlrev_b32_e32 v4, 1, v16
	v_or_b32_e32 v3, v30, v2
	v_and_b32_e32 v4, 48, v4
	v_sub_u32_e32 v3, v3, v4
	v_and_b32_e32 v4, 0xffffffc0, v16
	v_readlane_b32 s0, v254, 37
	v_sub_u32_e32 v3, v3, v4
	v_ashrrev_i32_e32 v20, 6, v16
	v_add3_u32 v26, v15, v2, s0
	v_mov_b32_e32 v2, 0
	v_and_b32_e32 v21, 63, v16
	v_add_u32_e32 v25, 0, v3
	s_mov_b32 s0, 0
	v_mov_b32_e32 v3, v2
	v_mov_b32_e32 v4, v2
	v_mov_b32_e32 v5, v2
	v_mov_b32_e32 v6, v2
	v_mov_b32_e32 v7, v2
	v_mov_b32_e32 v8, v2
	v_mov_b32_e32 v9, v2
	v_mov_b32_e32 v10, v2
	v_mov_b32_e32 v11, v2
	v_mov_b32_e32 v12, v2
	v_mov_b32_e32 v13, v2
	v_mov_b32_e32 v14, v2
	v_mov_b32_e32 v15, v2
	v_mov_b32_e32 v16, v2
	v_mov_b32_e32 v17, v2
	s_waitcnt lgkmcnt(0)
	s_barrier

.LBB0_653:
	s_or_b64 exec, exec, s[0:1]
	s_mov_b32 s0, 0x1000706
	v_lshl_add_u32 v0, v61, 4, 0
	s_waitcnt vmcnt(0)
	v_perm_b32 v12, v5, v6, s0
	v_perm_b32 v13, v6, v7, s0
	v_perm_b32 v14, v7, v8, s0
	v_pk_mov_b32 v[18:19], v[6:7], v[8:9] op_sel:[1,0]
	v_pk_mov_b32 v[16:17], v[4:5], v[6:7] op_sel:[1,0]
	v_perm_b32 v15, v8, v9, s0
	ds_write_b128 v0, v[16:19] offset:10368
	v_perm_b32 v18, v4, v5, s0
	v_mov_b32_e32 v19, v12
	v_mov_b32_e32 v20, v13
	v_mov_b32_e32 v21, v14
	ds_write_b128 v0, v[6:9]
	ds_write_b128 v0, v[12:15] offset:5184
	ds_write_b128 v0, v[18:21] offset:15552
	ds_write_b128 v0, v[4:7] offset:20736
	v_perm_b32 v6, v3, v4, s0
	v_mov_b32_e32 v7, v18
	v_mov_b32_e32 v8, v12
	v_mov_b32_e32 v9, v13
	v_pk_mov_b32 v[14:15], v[2:3], v[4:5] op_sel:[1,0]
	v_perm_b32 v2, v2, v3, s0
	v_mov_b32_e32 v3, v6
	v_mov_b32_e32 v4, v18
	v_mov_b32_e32 v5, v12
	ds_write_b128 v0, v[6:9] offset:25920
	ds_write_b128 v0, v[14:17] offset:31104
	ds_write_b128 v0, v[2:5] offset:36288

.LBB0_658:
	s_or_b64 exec, exec, s[8:9]
	global_load_ushort v82, v[2:3], off offset:528
	v_bfe_u32 v74, v61, 5, 1
	v_and_b32_e32 v4, 7, v61
	v_mad_i64_i32 v[68:69], s[8:9], v0, s4, 0
	v_and_b32_e32 v3, 0x7fffffd8, v61
	v_mul_u32_u24_e32 v4, 0x1440, v4
	v_mul_lo_u32 v17, v0, s60
	v_lshlrev_b32_e32 v0, 4, v74
	v_lshlrev_b32_e32 v81, 4, v61
	v_or_b32_e32 v4, v4, v0
	v_lshlrev_b32_e32 v3, 1, v3
	v_mad_i64_i32 v[70:71], s[8:9], v6, s4, 0
	v_and_b32_e32 v79, 31, v61
	v_and_b32_e32 v2, 0x1f0, v81
	v_sub_u32_e32 v3, v4, v3
	v_readlane_b32 s4, v254, 38
	v_add_u32_e32 v16, 0, v2
	v_mul_u32_u24_e32 v2, 0x210, v79
	s_waitcnt vmcnt(15)
	v_mul_lo_u32 v18, v6, s60
	v_add_u32_e32 v83, s4, v3
	v_readlane_b32 s4, v254, 37
	v_mov_b32_e32 v14, v1
	v_mov_b32_e32 v15, v1
	v_add3_u32 v84, v2, v0, s4
	v_mov_b32_e32 v0, v1
	v_mov_b32_e32 v2, v1
	v_mov_b32_e32 v3, v1
	v_mov_b32_e32 v4, v1
	v_mov_b32_e32 v5, v1
	v_mov_b32_e32 v6, v1
	v_mov_b32_e32 v7, v1
	v_mov_b32_e32 v8, v1
	v_mov_b32_e32 v9, v1
	v_mov_b32_e32 v10, v1
	v_mov_b32_e32 v11, v1
	v_mov_b32_e32 v12, v1
	v_mov_b32_e32 v13, v1
	v_add_u32_e32 v85, v16, v17
	v_add_u32_e32 v86, v16, v18
	s_waitcnt vmcnt(14)
	v_mov_b64_e32 v[30:31], v[14:15]
	v_mov_b64_e32 v[46:47], v[14:15]
	v_and_b32_e32 v80, 63, v61
	s_waitcnt vmcnt(11)
	v_mov_b32_e32 v66, v63
	v_mov_b32_e32 v67, v62
	v_mov_b32_e32 v64, v63
	s_mov_b32 s10, 0
	v_mov_b64_e32 v[28:29], v[12:13]
	v_mov_b64_e32 v[26:27], v[10:11]
	v_mov_b64_e32 v[24:25], v[8:9]
	v_mov_b64_e32 v[22:23], v[6:7]
	v_mov_b64_e32 v[20:21], v[4:5]
	v_mov_b64_e32 v[18:19], v[2:3]
	v_mov_b64_e32 v[16:17], v[0:1]
	v_mov_b64_e32 v[44:45], v[12:13]
	v_mov_b64_e32 v[42:43], v[10:11]
	v_mov_b64_e32 v[40:41], v[8:9]
	v_mov_b64_e32 v[38:39], v[6:7]
	v_mov_b64_e32 v[36:37], v[4:5]
	v_mov_b64_e32 v[34:35], v[2:3]
	v_mov_b64_e32 v[32:33], v[0:1]
.LBB0_659:
	s_waitcnt vmcnt(3)
	v_and_b32_e32 v4, 0xffff0000, v48
	v_lshlrev_b32_e32 v8, 16, v49
	v_lshlrev_b32_e32 v3, 16, v48
	v_mov_b32_e32 v2, v4
	v_mov_b32_e32 v10, v8
	v_mov_b32_e32 v11, v4
	s_waitcnt vmcnt(2)
	v_lshlrev_b32_e32 v0, 16, v76
	v_pk_mul_f32 v[6:7], v[64:65], v[2:3]
	v_pk_mul_f32 v[10:11], v[64:65], v[10:11]
	v_and_b32_e32 v5, 0xffff0000, v49
	v_fma_f32 v0, v62, v0, v7
	v_fma_f32 v2, v62, v3, v11
	v_add_f32_e32 v0, v6, v0
	v_pk_mul_f32 v[6:7], v[62:63], v[4:5]
	v_add_f32_e32 v2, v10, v2
	v_add_f32_e32 v12, v73, v2
	v_fma_f32 v2, v65, v8, v6
	v_lshlrev_b32_e32 v9, 16, v50
	v_add_f32_e32 v2, v7, v2
	v_add_f32_e32 v13, v73, v2
	v_pk_mul_f32 v[2:3], v[62:63], v[8:9]
	v_lshlrev_b32_e32 v6, 16, v51
	v_fma_f32 v2, v65, v5, v2
	v_add_f32_e32 v2, v3, v2
	v_add_f32_e32 v8, v73, v2
	v_and_b32_e32 v2, 0xffff0000, v50
	v_mov_b32_e32 v4, v2
	v_pk_mul_f32 v[4:5], v[66:67], v[4:5]
	v_mov_b32_e32 v10, v6
	v_fma_f32 v5, v65, v9, v5
	v_mov_b32_e32 v11, v2
	v_and_b32_e32 v3, 0xffff0000, v51
	v_add_f32_e32 v4, v4, v5
	v_pk_mul_f32 v[10:11], v[64:65], v[10:11]
	v_add_f32_e32 v14, v73, v4
	v_pk_mul_f32 v[4:5], v[62:63], v[2:3]
	v_fma_f32 v2, v62, v9, v11
	v_add_f32_e32 v2, v10, v2
	s_waitcnt vmcnt(2)
	v_lshlrev_b32_e32 v7, 16, v78
	v_add_f32_e32 v9, v73, v2
	v_fma_f32 v2, v65, v6, v4
	v_add_f32_e32 v2, v5, v2
	v_pk_mul_f32 v[4:5], v[62:63], v[6:7]
	v_add_f32_e32 v10, v73, v2
	v_fma_f32 v2, v65, v3, v4
	v_add_f32_e32 v2, v2, v5
	s_waitcnt lgkmcnt(0)
	s_barrier
	v_add_f32_e32 v0, v73, v0
	v_add_f32_e32 v5, v73, v2
	v_cvt_pk_bf16_f32 v2, v0, v12
	v_cvt_pk_bf16_f32 v3, v13, v8
	v_cvt_pk_bf16_f32 v4, v14, v9
	v_cvt_pk_bf16_f32 v5, v10, v5
	ds_write_b128 v85, v[2:5] offset:41472
	s_waitcnt vmcnt(1)
	v_and_b32_e32 v4, 0xffff0000, v52
	v_lshlrev_b32_e32 v8, 16, v53
	v_lshlrev_b32_e32 v3, 16, v52
	v_mov_b32_e32 v2, v4
	v_mov_b32_e32 v10, v8
	v_mov_b32_e32 v11, v4
	s_waitcnt vmcnt(0)
	v_lshlrev_b32_e32 v0, 16, v77
	v_pk_mul_f32 v[6:7], v[64:65], v[2:3]
	v_pk_mul_f32 v[10:11], v[64:65], v[10:11]
	v_and_b32_e32 v5, 0xffff0000, v53
	v_fma_f32 v0, v62, v0, v7
	v_fma_f32 v2, v62, v3, v11
	v_add_f32_e32 v0, v6, v0
	v_pk_mul_f32 v[6:7], v[62:63], v[4:5]
	v_add_f32_e32 v2, v10, v2
	v_add_f32_e32 v12, v73, v2
	v_fma_f32 v2, v65, v8, v6
	v_lshlrev_b32_e32 v9, 16, v54
	v_add_f32_e32 v2, v7, v2
	v_add_f32_e32 v13, v73, v2
	v_pk_mul_f32 v[2:3], v[62:63], v[8:9]
	v_lshlrev_b32_e32 v6, 16, v55
	v_fma_f32 v2, v65, v5, v2
	v_add_f32_e32 v2, v3, v2
	v_add_f32_e32 v8, v73, v2
	v_and_b32_e32 v2, 0xffff0000, v54
	v_mov_b32_e32 v4, v2
	v_pk_mul_f32 v[4:5], v[66:67], v[4:5]
	v_mov_b32_e32 v10, v6
	v_fma_f32 v5, v65, v9, v5
	v_mov_b32_e32 v11, v2
	v_and_b32_e32 v3, 0xffff0000, v55
	v_add_f32_e32 v4, v4, v5
	v_pk_mul_f32 v[10:11], v[64:65], v[10:11]
	v_add_f32_e32 v14, v73, v4
	v_pk_mul_f32 v[4:5], v[62:63], v[2:3]
	v_fma_f32 v2, v62, v9, v11
	v_add_f32_e32 v2, v10, v2
	s_waitcnt vmcnt(0)
	v_lshlrev_b32_e32 v7, 16, v82
	v_add_f32_e32 v9, v73, v2
	v_fma_f32 v2, v65, v6, v4
	v_add_f32_e32 v2, v5, v2
	v_pk_mul_f32 v[4:5], v[62:63], v[6:7]
	v_add_f32_e32 v10, v73, v2
	v_fma_f32 v2, v65, v3, v4
	v_add_f32_e32 v2, v2, v5
	s_mov_b32 s8, s10
	s_add_i32 s10, s10, 1
	v_add_f32_e32 v5, v73, v2
	s_cmp_eq_u32 s8, 7
	v_add_f32_e32 v0, v73, v0
	v_cvt_pk_bf16_f32 v2, v0, v12
	v_cvt_pk_bf16_f32 v3, v13, v8
	v_cvt_pk_bf16_f32 v4, v14, v9
	v_cvt_pk_bf16_f32 v5, v10, v5
	ds_write_b128 v86, v[2:5] offset:41472
	s_waitcnt lgkmcnt(0)
	s_barrier
	s_cbranch_scc1 .LBB0_665
	v_lshl_or_b32 v6, s10, 8, v75
	v_lshlrev_b32_e32 v0, 1, v6
	v_lshl_add_u64 v[2:3], s[0:1], 0, v[0:1]
	v_lshl_add_u64 v[4:5], v[2:3], 0, v[68:69]
	global_load_dwordx4 v[48:51], v[4:5], off offset:512
	global_load_ushort v76, v[4:5], off offset:510
	s_movk_i32 s8, 0x7f8
	v_cmp_ne_u32_e32 vcc, s8, v6
	v_mov_b32_e32 v82, 0
	v_mov_b32_e32 v78, 0
	s_and_saveexec_b64 s[8:9], vcc
	s_cbranch_execz .LBB0_662
	global_load_ushort v78, v[4:5], off offset:528

.LBB0_665:
	s_mov_b32 s8, 0
	ds_read_b128 v[2:5], v83
	ds_read_b128 v[6:9], v83 offset:32
	ds_read_b128 v[10:13], v83 offset:64
	ds_read_b128 v[240:243], v84
	ds_read_b128 v[88:91], v83 offset:96
	ds_read_b128 v[244:247], v84 offset:32
	ds_read_b128 v[236:239], v83 offset:128
	ds_read_b128 v[248:251], v84 offset:64
	s_waitcnt lgkmcnt(4)
	v_mfma_f32_32x32x16_bf16 v[32:47], v[10:13], v[240:243], v[32:47]
	v_mfma_f32_32x32x16_bf16 v[16:31], v[2:5], v[240:243], v[16:31]
	ds_read_b128 v[2:5], v83 offset:160
	ds_read_b128 v[240:243], v84 offset:96
	s_waitcnt lgkmcnt(4)
	v_mfma_f32_32x32x16_bf16 v[32:47], v[88:91], v[244:247], v[32:47]
	v_mfma_f32_32x32x16_bf16 v[16:31], v[6:9], v[244:247], v[16:31]
	ds_read_b128 v[6:9], v83 offset:192
	ds_read_b128 v[244:247], v84 offset:128
	s_waitcnt lgkmcnt(4)
	v_mfma_f32_32x32x16_bf16 v[32:47], v[236:239], v[248:251], v[32:47]
	v_mfma_f32_32x32x16_bf16 v[16:31], v[10:13], v[248:251], v[16:31]
	ds_read_b128 v[10:13], v83 offset:224
	ds_read_b128 v[248:251], v84 offset:160
	s_waitcnt lgkmcnt(4)
	v_mfma_f32_32x32x16_bf16 v[32:47], v[2:5], v[240:243], v[32:47]
	v_mfma_f32_32x32x16_bf16 v[16:31], v[88:91], v[240:243], v[16:31]
	ds_read_b128 v[88:91], v83 offset:256
	ds_read_b128 v[240:243], v84 offset:192
	s_waitcnt lgkmcnt(4)
	v_mfma_f32_32x32x16_bf16 v[32:47], v[6:9], v[244:247], v[32:47]
	v_mfma_f32_32x32x16_bf16 v[16:31], v[236:239], v[244:247], v[16:31]
	ds_read_b128 v[236:239], v83 offset:288
	ds_read_b128 v[244:247], v84 offset:224
	s_waitcnt lgkmcnt(4)
	v_mfma_f32_32x32x16_bf16 v[32:47], v[10:13], v[248:251], v[32:47]
	v_mfma_f32_32x32x16_bf16 v[16:31], v[2:5], v[248:251], v[16:31]
	ds_read_b128 v[2:5], v83 offset:320
	ds_read_b128 v[248:251], v84 offset:256
	s_waitcnt lgkmcnt(4)
	v_mfma_f32_32x32x16_bf16 v[32:47], v[88:91], v[240:243], v[32:47]
	v_mfma_f32_32x32x16_bf16 v[16:31], v[6:9], v[240:243], v[16:31]
	ds_read_b128 v[6:9], v83 offset:352
	ds_read_b128 v[240:243], v84 offset:288
	s_waitcnt lgkmcnt(4)
	v_mfma_f32_32x32x16_bf16 v[32:47], v[236:239], v[244:247], v[32:47]
	v_mfma_f32_32x32x16_bf16 v[16:31], v[10:13], v[244:247], v[16:31]
	ds_read_b128 v[10:13], v83 offset:384
	ds_read_b128 v[244:247], v84 offset:320
	s_waitcnt lgkmcnt(4)
	v_mfma_f32_32x32x16_bf16 v[32:47], v[2:5], v[248:251], v[32:47]
	v_mfma_f32_32x32x16_bf16 v[16:31], v[88:91], v[248:251], v[16:31]
	ds_read_b128 v[88:91], v83 offset:416
	ds_read_b128 v[248:251], v84 offset:352
	s_waitcnt lgkmcnt(4)
	v_mfma_f32_32x32x16_bf16 v[32:47], v[6:9], v[240:243], v[32:47]
	v_mfma_f32_32x32x16_bf16 v[16:31], v[236:239], v[240:243], v[16:31]
	ds_read_b128 v[236:239], v83 offset:448
	ds_read_b128 v[240:243], v84 offset:384
	s_waitcnt lgkmcnt(4)
	v_mfma_f32_32x32x16_bf16 v[32:47], v[10:13], v[244:247], v[32:47]
	v_mfma_f32_32x32x16_bf16 v[16:31], v[2:5], v[244:247], v[16:31]
	ds_read_b128 v[2:5], v83 offset:480
	ds_read_b128 v[244:247], v84 offset:416
	s_waitcnt lgkmcnt(4)
	v_mfma_f32_32x32x16_bf16 v[32:47], v[88:91], v[248:251], v[32:47]
	v_mfma_f32_32x32x16_bf16 v[16:31], v[6:9], v[248:251], v[16:31]
	ds_read_b128 v[6:9], v83 offset:512
	ds_read_b128 v[248:251], v84 offset:448
	s_waitcnt lgkmcnt(4)
	v_mfma_f32_32x32x16_bf16 v[32:47], v[236:239], v[240:243], v[32:47]
	v_mfma_f32_32x32x16_bf16 v[16:31], v[10:13], v[240:243], v[16:31]
	ds_read_b128 v[10:13], v83 offset:544
	ds_read_b128 v[240:243], v84 offset:480
	s_waitcnt lgkmcnt(4)
	v_mfma_f32_32x32x16_bf16 v[32:47], v[2:5], v[244:247], v[32:47]
	v_mfma_f32_32x32x16_bf16 v[16:31], v[88:91], v[244:247], v[16:31]
	s_waitcnt lgkmcnt(2)
	v_mfma_f32_32x32x16_bf16 v[32:47], v[6:9], v[248:251], v[32:47]
	v_mfma_f32_32x32x16_bf16 v[16:31], v[236:239], v[248:251], v[16:31]
	s_waitcnt lgkmcnt(0)
	v_mfma_f32_32x32x16_bf16 v[32:47], v[10:13], v[240:243], v[32:47]
	v_mfma_f32_32x32x16_bf16 v[16:31], v[2:5], v[240:243], v[16:31]
	s_cmp_lg_u32 s10, 8
	v_add_u32_e32 v83, 0x200, v83
	s_cbranch_scc1 .LBB0_659
	v_lshrrev_b32_e32 v0, 6, v61
	s_movk_i32 s0, 0x1080
	v_mul_lo_u32 v0, v0, s0
	s_add_i32 s0, 0, 0x10000
	s_waitcnt vmcnt(3)
	v_and_b32_e32 v50, 16, v81
	s_waitcnt vmcnt(1)
	v_add_u32_e32 v53, s0, v0
	v_lshrrev_b32_e32 v54, 1, v80
	v_or_b32_e32 v51, s12, v50
	v_lshl_add_u32 v52, v79, 2, v53
	v_mul_u32_u24_e32 v0, 0x900, v54
	v_or_b32_e32 v2, s6, v51
	v_mov_b32_e32 v3, s7
	v_lshl_add_u64 v[2:3], v[0:1], 0, v[2:3]
	s_mov_b64 s[0:1], 0x100
	v_mad_u32_u24 v0, v74, s60, v52
	v_and_b32_e32 v14, 0xffffffc0, v61
	v_lshl_add_u64 v[48:49], v[2:3], 0, s[0:1]
	v_add_u32_e32 v2, 0x400, v0
	ds_write2_b32 v0, v32, v33 offset1:33
	ds_write2_b32 v0, v34, v35 offset0:66 offset1:99
	ds_write2_b32 v2, v36, v37 offset0:8 offset1:41
	ds_write2_b32 v2, v38, v39 offset0:74 offset1:107
	v_add_u32_e32 v2, 0x800, v0
	v_add_u32_e32 v0, 0xc00, v0
	v_ashrrev_i32_e32 v15, 31, v14
	v_readlane_b32 s0, v254, 0
	ds_write2_b32 v2, v40, v41 offset0:16 offset1:49
	ds_write2_b32 v2, v42, v43 offset0:82 offset1:115
	ds_write2_b32 v0, v44, v45 offset0:24 offset1:57
	ds_write2_b32 v0, v46, v47 offset0:90 offset1:123
	v_lshl_add_u64 v[36:37], v[48:49], 0, v[14:15]
	v_readlane_b32 s1, v254, 1
	s_waitcnt lgkmcnt(0)
	v_add_u32_e32 v4, v51, v14
	v_cmp_lt_i32_e32 vcc, 0, v4
	v_lshl_add_u64 v[2:3], v[36:37], 1, s[0:1]
	global_load_dwordx4 v[10:13], v[2:3], off offset:16
	global_load_dwordx4 v[32:35], v[2:3], off
	v_mov_b32_e32 v0, 0
	v_mov_b32_e32 v38, 0
	s_and_saveexec_b64 s[0:1], vcc
	s_cbranch_execz .LBB0_670
	global_load_ushort v5, v[2:3], off offset:-2
	s_waitcnt vmcnt(0)
	v_lshlrev_b32_e32 v38, 16, v5

.LBB0_861:
	s_or_b64 exec, exec, s[14:15]
	s_mov_b32 s1, 0x1000706
	s_waitcnt vmcnt(0)
	v_perm_b32 v12, v5, v6, s1
	v_perm_b32 v13, v6, v7, s1
	v_perm_b32 v14, v7, v8, s1
	v_add_u32_e32 v11, 0, v18
	v_perm_b32 v15, v8, v9, s1
	v_pk_mov_b32 v[22:23], v[6:7], v[8:9] op_sel:[1,0]
	v_pk_mov_b32 v[20:21], v[4:5], v[6:7] op_sel:[1,0]
	v_perm_b32 v26, v4, v5, s1
	v_mov_b32_e32 v27, v12
	v_mov_b32_e32 v28, v13
	v_mov_b32_e32 v29, v14
	ds_write_b128 v11, v[6:9]
	ds_write_b128 v11, v[12:15] offset:5184
	ds_write_b128 v11, v[20:23] offset:10368
	ds_write_b128 v11, v[26:29] offset:15552
	ds_write_b128 v11, v[4:7] offset:20736
	v_perm_b32 v6, v3, v4, s1
	v_mov_b32_e32 v7, v26
	v_mov_b32_e32 v8, v12
	v_mov_b32_e32 v9, v13
	v_pk_mov_b32 v[14:15], v[2:3], v[4:5] op_sel:[1,0]
	v_mov_b32_e32 v16, v20
	v_mov_b32_e32 v17, v21
	v_perm_b32 v2, v2, v3, s1
	v_mov_b32_e32 v3, v6
	v_mov_b32_e32 v4, v26
	v_mov_b32_e32 v5, v12
	ds_write_b128 v11, v[6:9] offset:25920
	ds_write_b128 v11, v[14:17] offset:31104
	ds_write_b128 v11, v[2:5] offset:36288
.LBB0_862:
	s_or_b64 exec, exec, s[10:11]
	s_lshl_b64 s[10:11], s[6:7], 1
	v_readlane_b32 s4, v254, 2
	v_readlane_b32 s5, v254, 3
	s_add_u32 s10, s4, s10
	v_and_b32_e32 v0, 0xf8, v0
	s_addc_u32 s11, s5, s11
	v_lshlrev_b32_e32 v0, 1, v0
	v_lshl_add_u64 v[6:7], s[10:11], 0, v[0:1]
	v_ashrrev_i32_e32 v11, 5, v10
	s_movk_i32 s1, 0x1200
	v_add_u32_e32 v0, 0x200, v10
	v_mad_i64_i32 v[2:3], s[10:11], v11, s1, v[6:7]
	v_ashrrev_i32_e32 v14, 5, v0
	global_load_dwordx4 v[2:5], v[2:3], off
	v_mad_i64_i32 v[6:7], s[10:11], v14, s1, v[6:7]
	global_load_dwordx4 v[6:9], v[6:7], off
	v_and_b32_e32 v0, 0x1f0, v18
	v_add_u32_e32 v0, 0, v0
	v_and_b32_e32 v12, 7, v10
	v_mul_u32_u24_e32 v16, 0x1440, v12
	v_mad_u64_u32 v[12:13], s[10:11], v11, s60, v[0:1]
	v_bfe_u32 v20, v10, 5, 1
	s_waitcnt lgkmcnt(0)
	s_barrier
	v_and_b32_e32 v21, 31, v10
	v_mul_u32_u24_e32 v15, 0x210, v21
	v_readlane_b32 s1, v254, 37
	v_ashrrev_i32_e32 v19, 6, v10
	s_waitcnt vmcnt(8)
	v_and_b32_e32 v22, 63, v10
	s_waitcnt vmcnt(1)
	ds_write_b128 v12, v[2:5] offset:41472
	v_mad_u64_u32 v[2:3], s[10:11], v14, s60, v[0:1]
	s_waitcnt vmcnt(0)
	ds_write_b128 v2, v[6:9] offset:41472
	v_lshlrev_b32_e32 v2, 4, v20
	v_lshlrev_b32_e32 v3, 1, v10
	v_or_b32_e32 v0, v16, v2
	v_and_b32_e32 v3, 48, v3
	v_sub_u32_e32 v0, v0, v3
	v_and_b32_e32 v3, 0xffffffc0, v10
	v_sub_u32_e32 v0, v0, v3
	v_add3_u32 v23, v15, v2, s1
	v_mov_b32_e32 v2, 0
	v_add_u32_e32 v0, 0, v0
	s_mov_b32 s1, 0
	v_mov_b32_e32 v3, v2
	v_mov_b32_e32 v4, v2
	v_mov_b32_e32 v5, v2
	v_mov_b32_e32 v6, v2
	v_mov_b32_e32 v7, v2
	v_mov_b32_e32 v8, v2
	v_mov_b32_e32 v9, v2
	v_mov_b32_e32 v10, v2
	v_mov_b32_e32 v11, v2
	v_mov_b32_e32 v12, v2
	v_mov_b32_e32 v13, v2
	v_mov_b32_e32 v14, v2
	v_mov_b32_e32 v15, v2
	v_mov_b32_e32 v16, v2
	v_mov_b32_e32 v17, v2
	s_waitcnt lgkmcnt(0)
	s_barrier

.LBB0_877:
	s_or_b64 exec, exec, s[0:1]
	s_mov_b32 s0, 0x1000706
	v_add_u32_e32 v0, 0, v59
	s_waitcnt vmcnt(0)
	v_perm_b32 v12, v5, v6, s0
	v_perm_b32 v13, v6, v7, s0
	v_perm_b32 v14, v7, v8, s0
	v_pk_mov_b32 v[18:19], v[6:7], v[8:9] op_sel:[1,0]
	v_pk_mov_b32 v[16:17], v[4:5], v[6:7] op_sel:[1,0]
	v_perm_b32 v15, v8, v9, s0
	ds_write_b128 v0, v[16:19] offset:10368
	v_perm_b32 v18, v4, v5, s0
	v_mov_b32_e32 v19, v12
	v_mov_b32_e32 v20, v13
	v_mov_b32_e32 v21, v14
	ds_write_b128 v0, v[6:9]
	ds_write_b128 v0, v[12:15] offset:5184
	ds_write_b128 v0, v[18:21] offset:15552
	ds_write_b128 v0, v[4:7] offset:20736
	v_perm_b32 v6, v3, v4, s0
	v_mov_b32_e32 v7, v18
	v_mov_b32_e32 v8, v12
	v_mov_b32_e32 v9, v13
	v_pk_mov_b32 v[14:15], v[2:3], v[4:5] op_sel:[1,0]
	v_perm_b32 v2, v2, v3, s0
	v_mov_b32_e32 v3, v6
	v_mov_b32_e32 v4, v18
	v_mov_b32_e32 v5, v12
	ds_write_b128 v0, v[6:9] offset:25920
	ds_write_b128 v0, v[14:17] offset:31104
	ds_write_b128 v0, v[2:5] offset:36288
.LBB0_878:
	s_or_b64 exec, exec, s[10:11]
	s_lshl_b64 s[0:1], s[6:7], 1
	v_readlane_b32 s4, v254, 2
	v_readlane_b32 s5, v254, 3
	s_add_u32 s0, s4, s0
	v_and_b32_e32 v0, 0xf8, v10
	s_addc_u32 s1, s5, s1
	v_lshlrev_b32_e32 v0, 1, v0
	v_lshl_add_u64 v[48:49], s[0:1], 0, v[0:1]
	v_ashrrev_i32_e32 v10, 5, v46
	s_movk_i32 s4, 0x1200
	v_add_u32_e32 v0, 0x200, v46
	v_mad_i64_i32 v[54:55], s[0:1], v10, s4, v[48:49]
	v_ashrrev_i32_e32 v11, 5, v0
	s_waitcnt vmcnt(7)
	v_mad_i64_i32 v[56:57], s[0:1], v11, s4, v[48:49]
	global_load_dwordx4 v[2:5], v[54:55], off offset:512
	global_load_dwordx4 v[6:9], v[56:57], off offset:512
	v_and_b32_e32 v0, 0x1f0, v59
	v_add_u32_e32 v0, 0, v0
	v_mul_lo_u32 v12, v10, s60
	v_add_u32_e32 v63, v0, v12
	v_mul_lo_u32 v12, v11, s60
	v_add_u32_e32 v64, v0, v12
	s_waitcnt lgkmcnt(0)
	s_barrier
	s_waitcnt vmcnt(8)
	v_bfe_u32 v60, v46, 5, 1
	v_mad_i64_i32 v[52:53], s[0:1], v10, s4, 0
	v_mad_i64_i32 v[50:51], s[0:1], v11, s4, 0
	v_and_b32_e32 v0, 31, v46
	v_readlane_b32 s0, v254, 38
	v_and_b32_e32 v61, 63, v46
	s_waitcnt vmcnt(1)
	ds_write_b128 v63, v[2:5] offset:41472
	s_waitcnt vmcnt(0)
	ds_write_b128 v64, v[6:9] offset:41472
	s_waitcnt lgkmcnt(0)
	s_barrier
	global_load_dwordx4 v[34:37], v[54:55], off offset:1024
	global_load_dwordx4 v[38:41], v[56:57], off offset:1024
	v_and_b32_e32 v4, 7, v46
	v_and_b32_e32 v3, 0x7fffffd8, v46
	v_mul_u32_u24_e32 v4, 0x1440, v4
	v_lshlrev_b32_e32 v5, 4, v60
	v_or_b32_e32 v4, v4, v5
	v_lshlrev_b32_e32 v3, 1, v3
	v_sub_u32_e32 v65, v4, v3
	v_mul_u32_u24_e32 v2, 0x210, v0
	v_add_u32_e32 v66, s0, v65
	v_readlane_b32 s0, v254, 37
	s_nop 1
	v_add3_u32 v62, v2, v5, s0
	v_mov_b32_e32 v2, 0
	s_mov_b32 s0, 0
	v_mov_b32_e32 v3, v2
	v_mov_b32_e32 v4, v2
	v_mov_b32_e32 v5, v2
	v_mov_b32_e32 v6, v2
	v_mov_b32_e32 v7, v2
	v_mov_b32_e32 v8, v2
	v_mov_b32_e32 v9, v2
	v_mov_b32_e32 v10, v2
	v_mov_b32_e32 v11, v2
	v_mov_b32_e32 v12, v2
	v_mov_b32_e32 v13, v2
	v_mov_b32_e32 v14, v2
	v_mov_b32_e32 v15, v2
	v_mov_b32_e32 v16, v2
	v_mov_b32_e32 v17, v2
	v_mov_b32_e32 v18, v2
	v_mov_b32_e32 v19, v2
	v_mov_b32_e32 v20, v2
	v_mov_b32_e32 v21, v2
	v_mov_b32_e32 v22, v2
	v_mov_b32_e32 v23, v2
	v_mov_b32_e32 v24, v2
	v_mov_b32_e32 v25, v2
	v_mov_b32_e32 v26, v2
	v_mov_b32_e32 v27, v2
	v_mov_b32_e32 v28, v2
	v_mov_b32_e32 v29, v2
	v_mov_b32_e32 v30, v2
	v_mov_b32_e32 v31, v2
	v_mov_b32_e32 v32, v2
	v_mov_b32_e32 v33, v2
	ds_read_b128 v[68:71], v66
	ds_read_b128 v[72:75], v66 offset:32
	ds_read_b128 v[76:79], v66 offset:64
	ds_read_b128 v[240:243], v62
	ds_read_b128 v[80:83], v66 offset:96
	ds_read_b128 v[244:247], v62 offset:32
	ds_read_b128 v[236:239], v66 offset:128
	ds_read_b128 v[248:251], v62 offset:64
	s_waitcnt lgkmcnt(4)
	v_mfma_f32_32x32x16_bf16 v[18:33], v[76:79], v[240:243], v[18:33]
	v_mfma_f32_32x32x16_bf16 v[2:17], v[68:71], v[240:243], v[2:17]
	ds_read_b128 v[68:71], v66 offset:160
	ds_read_b128 v[240:243], v62 offset:96
	s_waitcnt lgkmcnt(4)
	v_mfma_f32_32x32x16_bf16 v[18:33], v[80:83], v[244:247], v[18:33]
	v_mfma_f32_32x32x16_bf16 v[2:17], v[72:75], v[244:247], v[2:17]
	ds_read_b128 v[72:75], v66 offset:192
	ds_read_b128 v[244:247], v62 offset:128
	s_waitcnt lgkmcnt(4)
	v_mfma_f32_32x32x16_bf16 v[18:33], v[236:239], v[248:251], v[18:33]
	v_mfma_f32_32x32x16_bf16 v[2:17], v[76:79], v[248:251], v[2:17]
	ds_read_b128 v[76:79], v66 offset:224
	ds_read_b128 v[248:251], v62 offset:160
	s_waitcnt lgkmcnt(4)
	v_mfma_f32_32x32x16_bf16 v[18:33], v[68:71], v[240:243], v[18:33]
	v_mfma_f32_32x32x16_bf16 v[2:17], v[80:83], v[240:243], v[2:17]
	ds_read_b128 v[80:83], v66 offset:256
	ds_read_b128 v[240:243], v62 offset:192
	s_waitcnt lgkmcnt(4)
	v_mfma_f32_32x32x16_bf16 v[18:33], v[72:75], v[244:247], v[18:33]
	v_mfma_f32_32x32x16_bf16 v[2:17], v[236:239], v[244:247], v[2:17]
	ds_read_b128 v[236:239], v66 offset:288
	ds_read_b128 v[244:247], v62 offset:224
	s_waitcnt lgkmcnt(4)
	v_mfma_f32_32x32x16_bf16 v[18:33], v[76:79], v[248:251], v[18:33]
	v_mfma_f32_32x32x16_bf16 v[2:17], v[68:71], v[248:251], v[2:17]
	ds_read_b128 v[68:71], v66 offset:320
	ds_read_b128 v[248:251], v62 offset:256
	s_waitcnt lgkmcnt(4)
	v_mfma_f32_32x32x16_bf16 v[18:33], v[80:83], v[240:243], v[18:33]
	v_mfma_f32_32x32x16_bf16 v[2:17], v[72:75], v[240:243], v[2:17]
	ds_read_b128 v[72:75], v66 offset:352
	ds_read_b128 v[240:243], v62 offset:288
	s_waitcnt lgkmcnt(4)
	v_mfma_f32_32x32x16_bf16 v[18:33], v[236:239], v[244:247], v[18:33]
	v_mfma_f32_32x32x16_bf16 v[2:17], v[76:79], v[244:247], v[2:17]
	ds_read_b128 v[76:79], v66 offset:384
	ds_read_b128 v[244:247], v62 offset:320
	s_waitcnt lgkmcnt(4)
	v_mfma_f32_32x32x16_bf16 v[18:33], v[68:71], v[248:251], v[18:33]
	v_mfma_f32_32x32x16_bf16 v[2:17], v[80:83], v[248:251], v[2:17]
	ds_read_b128 v[80:83], v66 offset:416
	ds_read_b128 v[248:251], v62 offset:352
	s_waitcnt lgkmcnt(4)
	v_mfma_f32_32x32x16_bf16 v[18:33], v[72:75], v[240:243], v[18:33]
	v_mfma_f32_32x32x16_bf16 v[2:17], v[236:239], v[240:243], v[2:17]
	ds_read_b128 v[236:239], v66 offset:448
	ds_read_b128 v[240:243], v62 offset:384
	s_waitcnt lgkmcnt(4)
	v_mfma_f32_32x32x16_bf16 v[18:33], v[76:79], v[244:247], v[18:33]
	v_mfma_f32_32x32x16_bf16 v[2:17], v[68:71], v[244:247], v[2:17]
	ds_read_b128 v[68:71], v66 offset:480
	ds_read_b128 v[244:247], v62 offset:416
	s_waitcnt lgkmcnt(4)
	v_mfma_f32_32x32x16_bf16 v[18:33], v[80:83], v[248:251], v[18:33]
	v_mfma_f32_32x32x16_bf16 v[2:17], v[72:75], v[248:251], v[2:17]
	ds_read_b128 v[72:75], v66 offset:512
	ds_read_b128 v[248:251], v62 offset:448
	s_waitcnt lgkmcnt(4)
	v_mfma_f32_32x32x16_bf16 v[18:33], v[236:239], v[240:243], v[18:33]
	v_mfma_f32_32x32x16_bf16 v[2:17], v[76:79], v[240:243], v[2:17]
	ds_read_b128 v[76:79], v66 offset:544
	ds_read_b128 v[240:243], v62 offset:480
	s_waitcnt lgkmcnt(4)
	v_mfma_f32_32x32x16_bf16 v[18:33], v[68:71], v[244:247], v[18:33]
	v_mfma_f32_32x32x16_bf16 v[2:17], v[80:83], v[244:247], v[2:17]
	s_waitcnt lgkmcnt(2)
	v_mfma_f32_32x32x16_bf16 v[18:33], v[72:75], v[248:251], v[18:33]
	v_mfma_f32_32x32x16_bf16 v[2:17], v[236:239], v[248:251], v[2:17]
	s_waitcnt lgkmcnt(0)
	v_mfma_f32_32x32x16_bf16 v[18:33], v[76:79], v[240:243], v[18:33]
	v_mfma_f32_32x32x16_bf16 v[2:17], v[68:71], v[240:243], v[2:17]
	s_barrier
	s_waitcnt vmcnt(1)
	ds_write_b128 v63, v[34:37] offset:41472
	s_waitcnt vmcnt(0)
	ds_write_b128 v64, v[38:41] offset:41472
	s_waitcnt lgkmcnt(0)
	s_barrier
	global_load_dwordx4 v[34:37], v[54:55], off offset:1536
	global_load_dwordx4 v[38:41], v[56:57], off offset:1536
	v_readlane_b32 s0, v254, 39
	s_nop 1
	v_add_u32_e32 v66, s0, v65
	s_mov_b32 s0, 0
	ds_read_b128 v[68:71], v66
	ds_read_b128 v[72:75], v66 offset:32
	ds_read_b128 v[76:79], v66 offset:64
	ds_read_b128 v[240:243], v62
	ds_read_b128 v[80:83], v66 offset:96
	ds_read_b128 v[244:247], v62 offset:32
	ds_read_b128 v[236:239], v66 offset:128
	ds_read_b128 v[248:251], v62 offset:64
	s_waitcnt lgkmcnt(4)
	v_mfma_f32_32x32x16_bf16 v[18:33], v[76:79], v[240:243], v[18:33]
	v_mfma_f32_32x32x16_bf16 v[2:17], v[68:71], v[240:243], v[2:17]
	ds_read_b128 v[68:71], v66 offset:160
	ds_read_b128 v[240:243], v62 offset:96
	s_waitcnt lgkmcnt(4)
	v_mfma_f32_32x32x16_bf16 v[18:33], v[80:83], v[244:247], v[18:33]
	v_mfma_f32_32x32x16_bf16 v[2:17], v[72:75], v[244:247], v[2:17]
	ds_read_b128 v[72:75], v66 offset:192
	ds_read_b128 v[244:247], v62 offset:128
	s_waitcnt lgkmcnt(4)
	v_mfma_f32_32x32x16_bf16 v[18:33], v[236:239], v[248:251], v[18:33]
	v_mfma_f32_32x32x16_bf16 v[2:17], v[76:79], v[248:251], v[2:17]
	ds_read_b128 v[76:79], v66 offset:224
	ds_read_b128 v[248:251], v62 offset:160
	s_waitcnt lgkmcnt(4)
	v_mfma_f32_32x32x16_bf16 v[18:33], v[68:71], v[240:243], v[18:33]
	v_mfma_f32_32x32x16_bf16 v[2:17], v[80:83], v[240:243], v[2:17]
	ds_read_b128 v[80:83], v66 offset:256
	ds_read_b128 v[240:243], v62 offset:192
	s_waitcnt lgkmcnt(4)
	v_mfma_f32_32x32x16_bf16 v[18:33], v[72:75], v[244:247], v[18:33]
	v_mfma_f32_32x32x16_bf16 v[2:17], v[236:239], v[244:247], v[2:17]
	ds_read_b128 v[236:239], v66 offset:288
	ds_read_b128 v[244:247], v62 offset:224
	s_waitcnt lgkmcnt(4)
	v_mfma_f32_32x32x16_bf16 v[18:33], v[76:79], v[248:251], v[18:33]
	v_mfma_f32_32x32x16_bf16 v[2:17], v[68:71], v[248:251], v[2:17]
	ds_read_b128 v[68:71], v66 offset:320
	ds_read_b128 v[248:251], v62 offset:256
	s_waitcnt lgkmcnt(4)
	v_mfma_f32_32x32x16_bf16 v[18:33], v[80:83], v[240:243], v[18:33]
	v_mfma_f32_32x32x16_bf16 v[2:17], v[72:75], v[240:243], v[2:17]
	ds_read_b128 v[72:75], v66 offset:352
	ds_read_b128 v[240:243], v62 offset:288
	s_waitcnt lgkmcnt(4)
	v_mfma_f32_32x32x16_bf16 v[18:33], v[236:239], v[244:247], v[18:33]
	v_mfma_f32_32x32x16_bf16 v[2:17], v[76:79], v[244:247], v[2:17]
	ds_read_b128 v[76:79], v66 offset:384
	ds_read_b128 v[244:247], v62 offset:320
	s_waitcnt lgkmcnt(4)
	v_mfma_f32_32x32x16_bf16 v[18:33], v[68:71], v[248:251], v[18:33]
	v_mfma_f32_32x32x16_bf16 v[2:17], v[80:83], v[248:251], v[2:17]
	ds_read_b128 v[80:83], v66 offset:416
	ds_read_b128 v[248:251], v62 offset:352
	s_waitcnt lgkmcnt(4)
	v_mfma_f32_32x32x16_bf16 v[18:33], v[72:75], v[240:243], v[18:33]
	v_mfma_f32_32x32x16_bf16 v[2:17], v[236:239], v[240:243], v[2:17]
	ds_read_b128 v[236:239], v66 offset:448
	ds_read_b128 v[240:243], v62 offset:384
	s_waitcnt lgkmcnt(4)
	v_mfma_f32_32x32x16_bf16 v[18:33], v[76:79], v[244:247], v[18:33]
	v_mfma_f32_32x32x16_bf16 v[2:17], v[68:71], v[244:247], v[2:17]
	ds_read_b128 v[68:71], v66 offset:480
	ds_read_b128 v[244:247], v62 offset:416
	s_waitcnt lgkmcnt(4)
	v_mfma_f32_32x32x16_bf16 v[18:33], v[80:83], v[248:251], v[18:33]
	v_mfma_f32_32x32x16_bf16 v[2:17], v[72:75], v[248:251], v[2:17]
	ds_read_b128 v[72:75], v66 offset:512
	ds_read_b128 v[248:251], v62 offset:448
	s_waitcnt lgkmcnt(4)
	v_mfma_f32_32x32x16_bf16 v[18:33], v[236:239], v[240:243], v[18:33]
	v_mfma_f32_32x32x16_bf16 v[2:17], v[76:79], v[240:243], v[2:17]
	ds_read_b128 v[76:79], v66 offset:544
	ds_read_b128 v[240:243], v62 offset:480
	s_waitcnt lgkmcnt(4)
	v_mfma_f32_32x32x16_bf16 v[18:33], v[68:71], v[244:247], v[18:33]
	v_mfma_f32_32x32x16_bf16 v[2:17], v[80:83], v[244:247], v[2:17]
	s_waitcnt lgkmcnt(2)
	v_mfma_f32_32x32x16_bf16 v[18:33], v[72:75], v[248:251], v[18:33]
	v_mfma_f32_32x32x16_bf16 v[2:17], v[236:239], v[248:251], v[2:17]
	s_waitcnt lgkmcnt(0)
	v_mfma_f32_32x32x16_bf16 v[18:33], v[76:79], v[240:243], v[18:33]
	v_mfma_f32_32x32x16_bf16 v[2:17], v[68:71], v[240:243], v[2:17]
	s_barrier
	s_waitcnt vmcnt(1)
	ds_write_b128 v63, v[34:37] offset:41472
	s_waitcnt vmcnt(0)
	ds_write_b128 v64, v[38:41] offset:41472
	s_waitcnt lgkmcnt(0)
	s_barrier
	global_load_dwordx4 v[34:37], v[54:55], off offset:2048
	global_load_dwordx4 v[38:41], v[56:57], off offset:2048
	v_readlane_b32 s0, v254, 40
	s_nop 1
	v_add_u32_e32 v66, s0, v65
	s_mov_b32 s0, 0
	ds_read_b128 v[68:71], v66
	ds_read_b128 v[72:75], v66 offset:32
	ds_read_b128 v[76:79], v66 offset:64
	ds_read_b128 v[240:243], v62
	ds_read_b128 v[80:83], v66 offset:96
	ds_read_b128 v[244:247], v62 offset:32
	ds_read_b128 v[236:239], v66 offset:128
	ds_read_b128 v[248:251], v62 offset:64
	s_waitcnt lgkmcnt(4)
	v_mfma_f32_32x32x16_bf16 v[18:33], v[76:79], v[240:243], v[18:33]
	v_mfma_f32_32x32x16_bf16 v[2:17], v[68:71], v[240:243], v[2:17]
	ds_read_b128 v[68:71], v66 offset:160
	ds_read_b128 v[240:243], v62 offset:96
	s_waitcnt lgkmcnt(4)
	v_mfma_f32_32x32x16_bf16 v[18:33], v[80:83], v[244:247], v[18:33]
	v_mfma_f32_32x32x16_bf16 v[2:17], v[72:75], v[244:247], v[2:17]
	ds_read_b128 v[72:75], v66 offset:192
	ds_read_b128 v[244:247], v62 offset:128
	s_waitcnt lgkmcnt(4)
	v_mfma_f32_32x32x16_bf16 v[18:33], v[236:239], v[248:251], v[18:33]
	v_mfma_f32_32x32x16_bf16 v[2:17], v[76:79], v[248:251], v[2:17]
	ds_read_b128 v[76:79], v66 offset:224
	ds_read_b128 v[248:251], v62 offset:160
	s_waitcnt lgkmcnt(4)
	v_mfma_f32_32x32x16_bf16 v[18:33], v[68:71], v[240:243], v[18:33]
	v_mfma_f32_32x32x16_bf16 v[2:17], v[80:83], v[240:243], v[2:17]
	ds_read_b128 v[80:83], v66 offset:256
	ds_read_b128 v[240:243], v62 offset:192
	s_waitcnt lgkmcnt(4)
	v_mfma_f32_32x32x16_bf16 v[18:33], v[72:75], v[244:247], v[18:33]
	v_mfma_f32_32x32x16_bf16 v[2:17], v[236:239], v[244:247], v[2:17]
	ds_read_b128 v[236:239], v66 offset:288
	ds_read_b128 v[244:247], v62 offset:224
	s_waitcnt lgkmcnt(4)
	v_mfma_f32_32x32x16_bf16 v[18:33], v[76:79], v[248:251], v[18:33]
	v_mfma_f32_32x32x16_bf16 v[2:17], v[68:71], v[248:251], v[2:17]
	ds_read_b128 v[68:71], v66 offset:320
	ds_read_b128 v[248:251], v62 offset:256
	s_waitcnt lgkmcnt(4)
	v_mfma_f32_32x32x16_bf16 v[18:33], v[80:83], v[240:243], v[18:33]
	v_mfma_f32_32x32x16_bf16 v[2:17], v[72:75], v[240:243], v[2:17]
	ds_read_b128 v[72:75], v66 offset:352
	ds_read_b128 v[240:243], v62 offset:288
	s_waitcnt lgkmcnt(4)
	v_mfma_f32_32x32x16_bf16 v[18:33], v[236:239], v[244:247], v[18:33]
	v_mfma_f32_32x32x16_bf16 v[2:17], v[76:79], v[244:247], v[2:17]
	ds_read_b128 v[76:79], v66 offset:384
	ds_read_b128 v[244:247], v62 offset:320
	s_waitcnt lgkmcnt(4)
	v_mfma_f32_32x32x16_bf16 v[18:33], v[68:71], v[248:251], v[18:33]
	v_mfma_f32_32x32x16_bf16 v[2:17], v[80:83], v[248:251], v[2:17]
	ds_read_b128 v[80:83], v66 offset:416
	ds_read_b128 v[248:251], v62 offset:352
	s_waitcnt lgkmcnt(4)
	v_mfma_f32_32x32x16_bf16 v[18:33], v[72:75], v[240:243], v[18:33]
	v_mfma_f32_32x32x16_bf16 v[2:17], v[236:239], v[240:243], v[2:17]
	ds_read_b128 v[236:239], v66 offset:448
	ds_read_b128 v[240:243], v62 offset:384
	s_waitcnt lgkmcnt(4)
	v_mfma_f32_32x32x16_bf16 v[18:33], v[76:79], v[244:247], v[18:33]
	v_mfma_f32_32x32x16_bf16 v[2:17], v[68:71], v[244:247], v[2:17]
	ds_read_b128 v[68:71], v66 offset:480
	ds_read_b128 v[244:247], v62 offset:416
	s_waitcnt lgkmcnt(4)
	v_mfma_f32_32x32x16_bf16 v[18:33], v[80:83], v[248:251], v[18:33]
	v_mfma_f32_32x32x16_bf16 v[2:17], v[72:75], v[248:251], v[2:17]
	ds_read_b128 v[72:75], v66 offset:512
	ds_read_b128 v[248:251], v62 offset:448
	s_waitcnt lgkmcnt(4)
	v_mfma_f32_32x32x16_bf16 v[18:33], v[236:239], v[240:243], v[18:33]
	v_mfma_f32_32x32x16_bf16 v[2:17], v[76:79], v[240:243], v[2:17]
	ds_read_b128 v[76:79], v66 offset:544
	ds_read_b128 v[240:243], v62 offset:480
	s_waitcnt lgkmcnt(4)
	v_mfma_f32_32x32x16_bf16 v[18:33], v[68:71], v[244:247], v[18:33]
	v_mfma_f32_32x32x16_bf16 v[2:17], v[80:83], v[244:247], v[2:17]
	s_waitcnt lgkmcnt(2)
	v_mfma_f32_32x32x16_bf16 v[18:33], v[72:75], v[248:251], v[18:33]
	v_mfma_f32_32x32x16_bf16 v[2:17], v[236:239], v[248:251], v[2:17]
	s_waitcnt lgkmcnt(0)
	v_mfma_f32_32x32x16_bf16 v[18:33], v[76:79], v[240:243], v[18:33]
	v_mfma_f32_32x32x16_bf16 v[2:17], v[68:71], v[240:243], v[2:17]
	s_barrier
	s_waitcnt vmcnt(1)
	ds_write_b128 v63, v[34:37] offset:41472
	s_waitcnt vmcnt(0)
	ds_write_b128 v64, v[38:41] offset:41472
	s_waitcnt lgkmcnt(0)
	s_barrier
	global_load_dwordx4 v[34:37], v[54:55], off offset:2560
	global_load_dwordx4 v[38:41], v[56:57], off offset:2560
	v_readlane_b32 s0, v254, 41
	s_nop 1
	v_add_u32_e32 v66, s0, v65
	s_mov_b32 s0, 0
	ds_read_b128 v[68:71], v66
	ds_read_b128 v[72:75], v66 offset:32
	ds_read_b128 v[76:79], v66 offset:64
	ds_read_b128 v[240:243], v62
	ds_read_b128 v[80:83], v66 offset:96
	ds_read_b128 v[244:247], v62 offset:32
	ds_read_b128 v[236:239], v66 offset:128
	ds_read_b128 v[248:251], v62 offset:64
	s_waitcnt lgkmcnt(4)
	v_mfma_f32_32x32x16_bf16 v[18:33], v[76:79], v[240:243], v[18:33]
	v_mfma_f32_32x32x16_bf16 v[2:17], v[68:71], v[240:243], v[2:17]
	ds_read_b128 v[68:71], v66 offset:160
	ds_read_b128 v[240:243], v62 offset:96
	s_waitcnt lgkmcnt(4)
	v_mfma_f32_32x32x16_bf16 v[18:33], v[80:83], v[244:247], v[18:33]
	v_mfma_f32_32x32x16_bf16 v[2:17], v[72:75], v[244:247], v[2:17]
	ds_read_b128 v[72:75], v66 offset:192
	ds_read_b128 v[244:247], v62 offset:128
	s_waitcnt lgkmcnt(4)
	v_mfma_f32_32x32x16_bf16 v[18:33], v[236:239], v[248:251], v[18:33]
	v_mfma_f32_32x32x16_bf16 v[2:17], v[76:79], v[248:251], v[2:17]
	ds_read_b128 v[76:79], v66 offset:224
	ds_read_b128 v[248:251], v62 offset:160
	s_waitcnt lgkmcnt(4)
	v_mfma_f32_32x32x16_bf16 v[18:33], v[68:71], v[240:243], v[18:33]
	v_mfma_f32_32x32x16_bf16 v[2:17], v[80:83], v[240:243], v[2:17]
	ds_read_b128 v[80:83], v66 offset:256
	ds_read_b128 v[240:243], v62 offset:192
	s_waitcnt lgkmcnt(4)
	v_mfma_f32_32x32x16_bf16 v[18:33], v[72:75], v[244:247], v[18:33]
	v_mfma_f32_32x32x16_bf16 v[2:17], v[236:239], v[244:247], v[2:17]
	ds_read_b128 v[236:239], v66 offset:288
	ds_read_b128 v[244:247], v62 offset:224
	s_waitcnt lgkmcnt(4)
	v_mfma_f32_32x32x16_bf16 v[18:33], v[76:79], v[248:251], v[18:33]
	v_mfma_f32_32x32x16_bf16 v[2:17], v[68:71], v[248:251], v[2:17]
	ds_read_b128 v[68:71], v66 offset:320
	ds_read_b128 v[248:251], v62 offset:256
	s_waitcnt lgkmcnt(4)
	v_mfma_f32_32x32x16_bf16 v[18:33], v[80:83], v[240:243], v[18:33]
	v_mfma_f32_32x32x16_bf16 v[2:17], v[72:75], v[240:243], v[2:17]
	ds_read_b128 v[72:75], v66 offset:352
	ds_read_b128 v[240:243], v62 offset:288
	s_waitcnt lgkmcnt(4)
	v_mfma_f32_32x32x16_bf16 v[18:33], v[236:239], v[244:247], v[18:33]
	v_mfma_f32_32x32x16_bf16 v[2:17], v[76:79], v[244:247], v[2:17]
	ds_read_b128 v[76:79], v66 offset:384
	ds_read_b128 v[244:247], v62 offset:320
	s_waitcnt lgkmcnt(4)
	v_mfma_f32_32x32x16_bf16 v[18:33], v[68:71], v[248:251], v[18:33]
	v_mfma_f32_32x32x16_bf16 v[2:17], v[80:83], v[248:251], v[2:17]
	ds_read_b128 v[80:83], v66 offset:416
	ds_read_b128 v[248:251], v62 offset:352
	s_waitcnt lgkmcnt(4)
	v_mfma_f32_32x32x16_bf16 v[18:33], v[72:75], v[240:243], v[18:33]
	v_mfma_f32_32x32x16_bf16 v[2:17], v[236:239], v[240:243], v[2:17]
	ds_read_b128 v[236:239], v66 offset:448
	ds_read_b128 v[240:243], v62 offset:384
	s_waitcnt lgkmcnt(4)
	v_mfma_f32_32x32x16_bf16 v[18:33], v[76:79], v[244:247], v[18:33]
	v_mfma_f32_32x32x16_bf16 v[2:17], v[68:71], v[244:247], v[2:17]
	ds_read_b128 v[68:71], v66 offset:480
	ds_read_b128 v[244:247], v62 offset:416
	s_waitcnt lgkmcnt(4)
	v_mfma_f32_32x32x16_bf16 v[18:33], v[80:83], v[248:251], v[18:33]
	v_mfma_f32_32x32x16_bf16 v[2:17], v[72:75], v[248:251], v[2:17]
	ds_read_b128 v[72:75], v66 offset:512
	ds_read_b128 v[248:251], v62 offset:448
	s_waitcnt lgkmcnt(4)
	v_mfma_f32_32x32x16_bf16 v[18:33], v[236:239], v[240:243], v[18:33]
	v_mfma_f32_32x32x16_bf16 v[2:17], v[76:79], v[240:243], v[2:17]
	ds_read_b128 v[76:79], v66 offset:544
	ds_read_b128 v[240:243], v62 offset:480
	s_waitcnt lgkmcnt(4)
	v_mfma_f32_32x32x16_bf16 v[18:33], v[68:71], v[244:247], v[18:33]
	v_mfma_f32_32x32x16_bf16 v[2:17], v[80:83], v[244:247], v[2:17]
	s_waitcnt lgkmcnt(2)
	v_mfma_f32_32x32x16_bf16 v[18:33], v[72:75], v[248:251], v[18:33]
	v_mfma_f32_32x32x16_bf16 v[2:17], v[236:239], v[248:251], v[2:17]
	s_waitcnt lgkmcnt(0)
	v_mfma_f32_32x32x16_bf16 v[18:33], v[76:79], v[240:243], v[18:33]
	v_mfma_f32_32x32x16_bf16 v[2:17], v[68:71], v[240:243], v[2:17]
	s_barrier
	s_waitcnt vmcnt(1)
	ds_write_b128 v63, v[34:37] offset:41472
	s_waitcnt vmcnt(0)
	ds_write_b128 v64, v[38:41] offset:41472
	s_waitcnt lgkmcnt(0)
	s_barrier
	global_load_dwordx4 v[34:37], v[54:55], off offset:3072
	global_load_dwordx4 v[38:41], v[56:57], off offset:3072
	v_readlane_b32 s0, v254, 42
	s_nop 1
	v_add_u32_e32 v66, s0, v65
	s_mov_b32 s0, 0
	ds_read_b128 v[68:71], v66
	ds_read_b128 v[72:75], v66 offset:32
	ds_read_b128 v[76:79], v66 offset:64
	ds_read_b128 v[240:243], v62
	ds_read_b128 v[80:83], v66 offset:96
	ds_read_b128 v[244:247], v62 offset:32
	ds_read_b128 v[236:239], v66 offset:128
	ds_read_b128 v[248:251], v62 offset:64
	s_waitcnt lgkmcnt(4)
	v_mfma_f32_32x32x16_bf16 v[18:33], v[76:79], v[240:243], v[18:33]
	v_mfma_f32_32x32x16_bf16 v[2:17], v[68:71], v[240:243], v[2:17]
	ds_read_b128 v[68:71], v66 offset:160
	ds_read_b128 v[240:243], v62 offset:96
	s_waitcnt lgkmcnt(4)
	v_mfma_f32_32x32x16_bf16 v[18:33], v[80:83], v[244:247], v[18:33]
	v_mfma_f32_32x32x16_bf16 v[2:17], v[72:75], v[244:247], v[2:17]
	ds_read_b128 v[72:75], v66 offset:192
	ds_read_b128 v[244:247], v62 offset:128
	s_waitcnt lgkmcnt(4)
	v_mfma_f32_32x32x16_bf16 v[18:33], v[236:239], v[248:251], v[18:33]
	v_mfma_f32_32x32x16_bf16 v[2:17], v[76:79], v[248:251], v[2:17]
	ds_read_b128 v[76:79], v66 offset:224
	ds_read_b128 v[248:251], v62 offset:160
	s_waitcnt lgkmcnt(4)
	v_mfma_f32_32x32x16_bf16 v[18:33], v[68:71], v[240:243], v[18:33]
	v_mfma_f32_32x32x16_bf16 v[2:17], v[80:83], v[240:243], v[2:17]
	ds_read_b128 v[80:83], v66 offset:256
	ds_read_b128 v[240:243], v62 offset:192
	s_waitcnt lgkmcnt(4)
	v_mfma_f32_32x32x16_bf16 v[18:33], v[72:75], v[244:247], v[18:33]
	v_mfma_f32_32x32x16_bf16 v[2:17], v[236:239], v[244:247], v[2:17]
	ds_read_b128 v[236:239], v66 offset:288
	ds_read_b128 v[244:247], v62 offset:224
	s_waitcnt lgkmcnt(4)
	v_mfma_f32_32x32x16_bf16 v[18:33], v[76:79], v[248:251], v[18:33]
	v_mfma_f32_32x32x16_bf16 v[2:17], v[68:71], v[248:251], v[2:17]
	ds_read_b128 v[68:71], v66 offset:320
	ds_read_b128 v[248:251], v62 offset:256
	s_waitcnt lgkmcnt(4)
	v_mfma_f32_32x32x16_bf16 v[18:33], v[80:83], v[240:243], v[18:33]
	v_mfma_f32_32x32x16_bf16 v[2:17], v[72:75], v[240:243], v[2:17]
	ds_read_b128 v[72:75], v66 offset:352
	ds_read_b128 v[240:243], v62 offset:288
	s_waitcnt lgkmcnt(4)
	v_mfma_f32_32x32x16_bf16 v[18:33], v[236:239], v[244:247], v[18:33]
	v_mfma_f32_32x32x16_bf16 v[2:17], v[76:79], v[244:247], v[2:17]
	ds_read_b128 v[76:79], v66 offset:384
	ds_read_b128 v[244:247], v62 offset:320
	s_waitcnt lgkmcnt(4)
	v_mfma_f32_32x32x16_bf16 v[18:33], v[68:71], v[248:251], v[18:33]
	v_mfma_f32_32x32x16_bf16 v[2:17], v[80:83], v[248:251], v[2:17]
	ds_read_b128 v[80:83], v66 offset:416
	ds_read_b128 v[248:251], v62 offset:352
	s_waitcnt lgkmcnt(4)
	v_mfma_f32_32x32x16_bf16 v[18:33], v[72:75], v[240:243], v[18:33]
	v_mfma_f32_32x32x16_bf16 v[2:17], v[236:239], v[240:243], v[2:17]
	ds_read_b128 v[236:239], v66 offset:448
	ds_read_b128 v[240:243], v62 offset:384
	s_waitcnt lgkmcnt(4)
	v_mfma_f32_32x32x16_bf16 v[18:33], v[76:79], v[244:247], v[18:33]
	v_mfma_f32_32x32x16_bf16 v[2:17], v[68:71], v[244:247], v[2:17]
	ds_read_b128 v[68:71], v66 offset:480
	ds_read_b128 v[244:247], v62 offset:416
	s_waitcnt lgkmcnt(4)
	v_mfma_f32_32x32x16_bf16 v[18:33], v[80:83], v[248:251], v[18:33]
	v_mfma_f32_32x32x16_bf16 v[2:17], v[72:75], v[248:251], v[2:17]
	ds_read_b128 v[72:75], v66 offset:512
	ds_read_b128 v[248:251], v62 offset:448
	s_waitcnt lgkmcnt(4)
	v_mfma_f32_32x32x16_bf16 v[18:33], v[236:239], v[240:243], v[18:33]
	v_mfma_f32_32x32x16_bf16 v[2:17], v[76:79], v[240:243], v[2:17]
	ds_read_b128 v[76:79], v66 offset:544
	ds_read_b128 v[240:243], v62 offset:480
	s_waitcnt lgkmcnt(4)
	v_mfma_f32_32x32x16_bf16 v[18:33], v[68:71], v[244:247], v[18:33]
	v_mfma_f32_32x32x16_bf16 v[2:17], v[80:83], v[244:247], v[2:17]
	s_waitcnt lgkmcnt(2)
	v_mfma_f32_32x32x16_bf16 v[18:33], v[72:75], v[248:251], v[18:33]
	v_mfma_f32_32x32x16_bf16 v[2:17], v[236:239], v[248:251], v[2:17]
	s_waitcnt lgkmcnt(0)
	v_mfma_f32_32x32x16_bf16 v[18:33], v[76:79], v[240:243], v[18:33]
	v_mfma_f32_32x32x16_bf16 v[2:17], v[68:71], v[240:243], v[2:17]
	s_barrier
	s_waitcnt vmcnt(1)
	ds_write_b128 v63, v[34:37] offset:41472
	s_waitcnt vmcnt(0)
	ds_write_b128 v64, v[38:41] offset:41472
	s_waitcnt lgkmcnt(0)
	s_barrier
	global_load_dwordx4 v[34:37], v[54:55], off offset:3584
	global_load_dwordx4 v[38:41], v[56:57], off offset:3584
	v_readlane_b32 s0, v254, 43
	s_nop 1
	v_add_u32_e32 v54, s0, v65
	s_mov_b32 s0, 0
	ds_read_b128 v[66:69], v54
	ds_read_b128 v[70:73], v54 offset:32
	ds_read_b128 v[74:77], v54 offset:64
	ds_read_b128 v[240:243], v62
	ds_read_b128 v[78:81], v54 offset:96
	ds_read_b128 v[244:247], v62 offset:32
	ds_read_b128 v[236:239], v54 offset:128
	ds_read_b128 v[248:251], v62 offset:64
	s_waitcnt lgkmcnt(4)
	v_mfma_f32_32x32x16_bf16 v[18:33], v[74:77], v[240:243], v[18:33]
	v_mfma_f32_32x32x16_bf16 v[2:17], v[66:69], v[240:243], v[2:17]
	ds_read_b128 v[66:69], v54 offset:160
	ds_read_b128 v[240:243], v62 offset:96
	s_waitcnt lgkmcnt(4)
	v_mfma_f32_32x32x16_bf16 v[18:33], v[78:81], v[244:247], v[18:33]
	v_mfma_f32_32x32x16_bf16 v[2:17], v[70:73], v[244:247], v[2:17]
	ds_read_b128 v[70:73], v54 offset:192
	ds_read_b128 v[244:247], v62 offset:128
	s_waitcnt lgkmcnt(4)
	v_mfma_f32_32x32x16_bf16 v[18:33], v[236:239], v[248:251], v[18:33]
	v_mfma_f32_32x32x16_bf16 v[2:17], v[74:77], v[248:251], v[2:17]
	ds_read_b128 v[74:77], v54 offset:224
	ds_read_b128 v[248:251], v62 offset:160
	s_waitcnt lgkmcnt(4)
	v_mfma_f32_32x32x16_bf16 v[18:33], v[66:69], v[240:243], v[18:33]
	v_mfma_f32_32x32x16_bf16 v[2:17], v[78:81], v[240:243], v[2:17]
	ds_read_b128 v[78:81], v54 offset:256
	ds_read_b128 v[240:243], v62 offset:192
	s_waitcnt lgkmcnt(4)
	v_mfma_f32_32x32x16_bf16 v[18:33], v[70:73], v[244:247], v[18:33]
	v_mfma_f32_32x32x16_bf16 v[2:17], v[236:239], v[244:247], v[2:17]
	ds_read_b128 v[236:239], v54 offset:288
	ds_read_b128 v[244:247], v62 offset:224
	s_waitcnt lgkmcnt(4)
	v_mfma_f32_32x32x16_bf16 v[18:33], v[74:77], v[248:251], v[18:33]
	v_mfma_f32_32x32x16_bf16 v[2:17], v[66:69], v[248:251], v[2:17]
	ds_read_b128 v[66:69], v54 offset:320
	ds_read_b128 v[248:251], v62 offset:256
	s_waitcnt lgkmcnt(4)
	v_mfma_f32_32x32x16_bf16 v[18:33], v[78:81], v[240:243], v[18:33]
	v_mfma_f32_32x32x16_bf16 v[2:17], v[70:73], v[240:243], v[2:17]
	ds_read_b128 v[70:73], v54 offset:352
	ds_read_b128 v[240:243], v62 offset:288
	s_waitcnt lgkmcnt(4)
	v_mfma_f32_32x32x16_bf16 v[18:33], v[236:239], v[244:247], v[18:33]
	v_mfma_f32_32x32x16_bf16 v[2:17], v[74:77], v[244:247], v[2:17]
	ds_read_b128 v[74:77], v54 offset:384
	ds_read_b128 v[244:247], v62 offset:320
	s_waitcnt lgkmcnt(4)
	v_mfma_f32_32x32x16_bf16 v[18:33], v[66:69], v[248:251], v[18:33]
	v_mfma_f32_32x32x16_bf16 v[2:17], v[78:81], v[248:251], v[2:17]
	ds_read_b128 v[78:81], v54 offset:416
	ds_read_b128 v[248:251], v62 offset:352
	s_waitcnt lgkmcnt(4)
	v_mfma_f32_32x32x16_bf16 v[18:33], v[70:73], v[240:243], v[18:33]
	v_mfma_f32_32x32x16_bf16 v[2:17], v[236:239], v[240:243], v[2:17]
	ds_read_b128 v[236:239], v54 offset:448
	ds_read_b128 v[240:243], v62 offset:384
	s_waitcnt lgkmcnt(4)
	v_mfma_f32_32x32x16_bf16 v[18:33], v[74:77], v[244:247], v[18:33]
	v_mfma_f32_32x32x16_bf16 v[2:17], v[66:69], v[244:247], v[2:17]
	ds_read_b128 v[66:69], v54 offset:480
	ds_read_b128 v[244:247], v62 offset:416
	s_waitcnt lgkmcnt(4)
	v_mfma_f32_32x32x16_bf16 v[18:33], v[78:81], v[248:251], v[18:33]
	v_mfma_f32_32x32x16_bf16 v[2:17], v[70:73], v[248:251], v[2:17]
	ds_read_b128 v[70:73], v54 offset:512
	ds_read_b128 v[248:251], v62 offset:448
	s_waitcnt lgkmcnt(4)
	v_mfma_f32_32x32x16_bf16 v[18:33], v[236:239], v[240:243], v[18:33]
	v_mfma_f32_32x32x16_bf16 v[2:17], v[74:77], v[240:243], v[2:17]
	ds_read_b128 v[74:77], v54 offset:544
	ds_read_b128 v[240:243], v62 offset:480
	s_waitcnt lgkmcnt(4)
	v_mfma_f32_32x32x16_bf16 v[18:33], v[66:69], v[244:247], v[18:33]
	v_mfma_f32_32x32x16_bf16 v[2:17], v[78:81], v[244:247], v[2:17]
	s_waitcnt lgkmcnt(2)
	v_mfma_f32_32x32x16_bf16 v[18:33], v[70:73], v[248:251], v[18:33]
	v_mfma_f32_32x32x16_bf16 v[2:17], v[236:239], v[248:251], v[2:17]
	s_waitcnt lgkmcnt(0)
	v_mfma_f32_32x32x16_bf16 v[18:33], v[74:77], v[240:243], v[18:33]
	v_mfma_f32_32x32x16_bf16 v[2:17], v[66:69], v[240:243], v[2:17]
	s_mov_b64 s[0:1], 0x200
	v_lshl_add_u64 v[48:49], v[48:49], 0, s[0:1]
	s_barrier
	s_waitcnt vmcnt(1)
	ds_write_b128 v63, v[34:37] offset:41472
	s_waitcnt vmcnt(0)
	ds_write_b128 v64, v[38:41] offset:41472
	v_lshl_add_u64 v[34:35], v[48:49], 0, v[52:53]
	v_lshl_add_u64 v[38:39], v[48:49], 0, v[50:51]
	s_waitcnt lgkmcnt(0)
	s_barrier
	global_load_dwordx4 v[34:37], v[34:35], off offset:3584
	s_nop 0
	global_load_dwordx4 v[38:41], v[38:39], off offset:3584
	v_readlane_b32 s0, v254, 44
	s_nop 1
	v_add_u32_e32 v48, s0, v65
	s_mov_b32 s0, 0
	ds_read_b128 v[50:53], v48
	ds_read_b128 v[54:57], v48 offset:32
	ds_read_b128 v[66:69], v48 offset:64
	ds_read_b128 v[240:243], v62
	ds_read_b128 v[70:73], v48 offset:96
	ds_read_b128 v[244:247], v62 offset:32
	ds_read_b128 v[236:239], v48 offset:128
	ds_read_b128 v[248:251], v62 offset:64
	s_waitcnt lgkmcnt(4)
	v_mfma_f32_32x32x16_bf16 v[18:33], v[66:69], v[240:243], v[18:33]
	v_mfma_f32_32x32x16_bf16 v[2:17], v[50:53], v[240:243], v[2:17]
	ds_read_b128 v[50:53], v48 offset:160
	ds_read_b128 v[240:243], v62 offset:96
	s_waitcnt lgkmcnt(4)
	v_mfma_f32_32x32x16_bf16 v[18:33], v[70:73], v[244:247], v[18:33]
	v_mfma_f32_32x32x16_bf16 v[2:17], v[54:57], v[244:247], v[2:17]
	ds_read_b128 v[54:57], v48 offset:192
	ds_read_b128 v[244:247], v62 offset:128
	s_waitcnt lgkmcnt(4)
	v_mfma_f32_32x32x16_bf16 v[18:33], v[236:239], v[248:251], v[18:33]
	v_mfma_f32_32x32x16_bf16 v[2:17], v[66:69], v[248:251], v[2:17]
	ds_read_b128 v[66:69], v48 offset:224
	ds_read_b128 v[248:251], v62 offset:160
	s_waitcnt lgkmcnt(4)
	v_mfma_f32_32x32x16_bf16 v[18:33], v[50:53], v[240:243], v[18:33]
	v_mfma_f32_32x32x16_bf16 v[2:17], v[70:73], v[240:243], v[2:17]
	ds_read_b128 v[70:73], v48 offset:256
	ds_read_b128 v[240:243], v62 offset:192
	s_waitcnt lgkmcnt(4)
	v_mfma_f32_32x32x16_bf16 v[18:33], v[54:57], v[244:247], v[18:33]
	v_mfma_f32_32x32x16_bf16 v[2:17], v[236:239], v[244:247], v[2:17]
	ds_read_b128 v[236:239], v48 offset:288
	ds_read_b128 v[244:247], v62 offset:224
	s_waitcnt lgkmcnt(4)
	v_mfma_f32_32x32x16_bf16 v[18:33], v[66:69], v[248:251], v[18:33]
	v_mfma_f32_32x32x16_bf16 v[2:17], v[50:53], v[248:251], v[2:17]
	ds_read_b128 v[50:53], v48 offset:320
	ds_read_b128 v[248:251], v62 offset:256
	s_waitcnt lgkmcnt(4)
	v_mfma_f32_32x32x16_bf16 v[18:33], v[70:73], v[240:243], v[18:33]
	v_mfma_f32_32x32x16_bf16 v[2:17], v[54:57], v[240:243], v[2:17]
	ds_read_b128 v[54:57], v48 offset:352
	ds_read_b128 v[240:243], v62 offset:288
	s_waitcnt lgkmcnt(4)
	v_mfma_f32_32x32x16_bf16 v[18:33], v[236:239], v[244:247], v[18:33]
	v_mfma_f32_32x32x16_bf16 v[2:17], v[66:69], v[244:247], v[2:17]
	ds_read_b128 v[66:69], v48 offset:384
	ds_read_b128 v[244:247], v62 offset:320
	s_waitcnt lgkmcnt(4)
	v_mfma_f32_32x32x16_bf16 v[18:33], v[50:53], v[248:251], v[18:33]
	v_mfma_f32_32x32x16_bf16 v[2:17], v[70:73], v[248:251], v[2:17]
	ds_read_b128 v[70:73], v48 offset:416
	ds_read_b128 v[248:251], v62 offset:352
	s_waitcnt lgkmcnt(4)
	v_mfma_f32_32x32x16_bf16 v[18:33], v[54:57], v[240:243], v[18:33]
	v_mfma_f32_32x32x16_bf16 v[2:17], v[236:239], v[240:243], v[2:17]
	ds_read_b128 v[236:239], v48 offset:448
	ds_read_b128 v[240:243], v62 offset:384
	s_waitcnt lgkmcnt(4)
	v_mfma_f32_32x32x16_bf16 v[18:33], v[66:69], v[244:247], v[18:33]
	v_mfma_f32_32x32x16_bf16 v[2:17], v[50:53], v[244:247], v[2:17]
	ds_read_b128 v[50:53], v48 offset:480
	ds_read_b128 v[244:247], v62 offset:416
	s_waitcnt lgkmcnt(4)
	v_mfma_f32_32x32x16_bf16 v[18:33], v[70:73], v[248:251], v[18:33]
	v_mfma_f32_32x32x16_bf16 v[2:17], v[54:57], v[248:251], v[2:17]
	ds_read_b128 v[54:57], v48 offset:512
	ds_read_b128 v[248:251], v62 offset:448
	s_waitcnt lgkmcnt(4)
	v_mfma_f32_32x32x16_bf16 v[18:33], v[236:239], v[240:243], v[18:33]
	v_mfma_f32_32x32x16_bf16 v[2:17], v[66:69], v[240:243], v[2:17]
	ds_read_b128 v[66:69], v48 offset:544
	ds_read_b128 v[240:243], v62 offset:480
	s_waitcnt lgkmcnt(4)
	v_mfma_f32_32x32x16_bf16 v[18:33], v[50:53], v[244:247], v[18:33]
	v_mfma_f32_32x32x16_bf16 v[2:17], v[70:73], v[244:247], v[2:17]
	s_waitcnt lgkmcnt(2)
	v_mfma_f32_32x32x16_bf16 v[18:33], v[54:57], v[248:251], v[18:33]
	v_mfma_f32_32x32x16_bf16 v[2:17], v[236:239], v[248:251], v[2:17]
	s_waitcnt lgkmcnt(0)
	v_mfma_f32_32x32x16_bf16 v[18:33], v[66:69], v[240:243], v[18:33]
	v_mfma_f32_32x32x16_bf16 v[2:17], v[50:53], v[240:243], v[2:17]
	v_readlane_b32 s0, v254, 45
	s_barrier
	s_waitcnt vmcnt(1)
	ds_write_b128 v63, v[34:37] offset:41472
	s_waitcnt vmcnt(0)
	ds_write_b128 v64, v[38:41] offset:41472
	v_add_u32_e32 v34, s0, v65
	s_mov_b32 s0, 0
	s_waitcnt lgkmcnt(0)
	s_barrier
	ds_read_b128 v[36:39], v34
	ds_read_b128 v[48:51], v34 offset:32
	ds_read_b128 v[52:55], v34 offset:64
	ds_read_b128 v[240:243], v62
	ds_read_b128 v[64:67], v34 offset:96
	ds_read_b128 v[244:247], v62 offset:32
	ds_read_b128 v[236:239], v34 offset:128
	ds_read_b128 v[248:251], v62 offset:64
	s_waitcnt lgkmcnt(4)
	v_mfma_f32_32x32x16_bf16 v[18:33], v[52:55], v[240:243], v[18:33]
	v_mfma_f32_32x32x16_bf16 v[2:17], v[36:39], v[240:243], v[2:17]
	ds_read_b128 v[36:39], v34 offset:160
	ds_read_b128 v[240:243], v62 offset:96
	s_waitcnt lgkmcnt(4)
	v_mfma_f32_32x32x16_bf16 v[18:33], v[64:67], v[244:247], v[18:33]
	v_mfma_f32_32x32x16_bf16 v[2:17], v[48:51], v[244:247], v[2:17]
	ds_read_b128 v[48:51], v34 offset:192
	ds_read_b128 v[244:247], v62 offset:128
	s_waitcnt lgkmcnt(4)
	v_mfma_f32_32x32x16_bf16 v[18:33], v[236:239], v[248:251], v[18:33]
	v_mfma_f32_32x32x16_bf16 v[2:17], v[52:55], v[248:251], v[2:17]
	ds_read_b128 v[52:55], v34 offset:224
	ds_read_b128 v[248:251], v62 offset:160
	s_waitcnt lgkmcnt(4)
	v_mfma_f32_32x32x16_bf16 v[18:33], v[36:39], v[240:243], v[18:33]
	v_mfma_f32_32x32x16_bf16 v[2:17], v[64:67], v[240:243], v[2:17]
	ds_read_b128 v[64:67], v34 offset:256
	ds_read_b128 v[240:243], v62 offset:192
	s_waitcnt lgkmcnt(4)
	v_mfma_f32_32x32x16_bf16 v[18:33], v[48:51], v[244:247], v[18:33]
	v_mfma_f32_32x32x16_bf16 v[2:17], v[236:239], v[244:247], v[2:17]
	ds_read_b128 v[236:239], v34 offset:288
	ds_read_b128 v[244:247], v62 offset:224
	s_waitcnt lgkmcnt(4)
	v_mfma_f32_32x32x16_bf16 v[18:33], v[52:55], v[248:251], v[18:33]
	v_mfma_f32_32x32x16_bf16 v[2:17], v[36:39], v[248:251], v[2:17]
	ds_read_b128 v[36:39], v34 offset:320
	ds_read_b128 v[248:251], v62 offset:256
	s_waitcnt lgkmcnt(4)
	v_mfma_f32_32x32x16_bf16 v[18:33], v[64:67], v[240:243], v[18:33]
	v_mfma_f32_32x32x16_bf16 v[2:17], v[48:51], v[240:243], v[2:17]
	ds_read_b128 v[48:51], v34 offset:352
	ds_read_b128 v[240:243], v62 offset:288
	s_waitcnt lgkmcnt(4)
	v_mfma_f32_32x32x16_bf16 v[18:33], v[236:239], v[244:247], v[18:33]
	v_mfma_f32_32x32x16_bf16 v[2:17], v[52:55], v[244:247], v[2:17]
	ds_read_b128 v[52:55], v34 offset:384
	ds_read_b128 v[244:247], v62 offset:320
	s_waitcnt lgkmcnt(4)
	v_mfma_f32_32x32x16_bf16 v[18:33], v[36:39], v[248:251], v[18:33]
	v_mfma_f32_32x32x16_bf16 v[2:17], v[64:67], v[248:251], v[2:17]
	ds_read_b128 v[64:67], v34 offset:416
	ds_read_b128 v[248:251], v62 offset:352
	s_waitcnt lgkmcnt(4)
	v_mfma_f32_32x32x16_bf16 v[18:33], v[48:51], v[240:243], v[18:33]
	v_mfma_f32_32x32x16_bf16 v[2:17], v[236:239], v[240:243], v[2:17]
	ds_read_b128 v[236:239], v34 offset:448
	ds_read_b128 v[240:243], v62 offset:384
	s_waitcnt lgkmcnt(4)
	v_mfma_f32_32x32x16_bf16 v[18:33], v[52:55], v[244:247], v[18:33]
	v_mfma_f32_32x32x16_bf16 v[2:17], v[36:39], v[244:247], v[2:17]
	ds_read_b128 v[36:39], v34 offset:480
	ds_read_b128 v[244:247], v62 offset:416
	s_waitcnt lgkmcnt(4)
	v_mfma_f32_32x32x16_bf16 v[18:33], v[64:67], v[248:251], v[18:33]
	v_mfma_f32_32x32x16_bf16 v[2:17], v[48:51], v[248:251], v[2:17]
	ds_read_b128 v[48:51], v34 offset:512
	ds_read_b128 v[248:251], v62 offset:448
	s_waitcnt lgkmcnt(4)
	v_mfma_f32_32x32x16_bf16 v[18:33], v[236:239], v[240:243], v[18:33]
	v_mfma_f32_32x32x16_bf16 v[2:17], v[52:55], v[240:243], v[2:17]
	ds_read_b128 v[52:55], v34 offset:544
	ds_read_b128 v[240:243], v62 offset:480
	s_waitcnt lgkmcnt(4)
	v_mfma_f32_32x32x16_bf16 v[18:33], v[36:39], v[244:247], v[18:33]
	v_mfma_f32_32x32x16_bf16 v[2:17], v[64:67], v[244:247], v[2:17]
	s_waitcnt lgkmcnt(2)
	v_mfma_f32_32x32x16_bf16 v[18:33], v[48:51], v[248:251], v[18:33]
	v_mfma_f32_32x32x16_bf16 v[2:17], v[236:239], v[248:251], v[2:17]
	s_waitcnt lgkmcnt(0)
	v_mfma_f32_32x32x16_bf16 v[18:33], v[52:55], v[240:243], v[18:33]
	v_mfma_f32_32x32x16_bf16 v[2:17], v[36:39], v[240:243], v[2:17]
	v_lshrrev_b32_e32 v34, 6, v46
	s_movk_i32 s0, 0x1080
	v_mul_lo_u32 v34, v34, s0
	s_add_i32 s0, 0, 0x10000
	v_and_b32_e32 v48, 16, v59
	v_add_u32_e32 v40, s0, v34
	v_lshrrev_b32_e32 v51, 1, v61
	v_or_b32_e32 v49, s12, v48
	v_lshl_add_u32 v50, v0, 2, v40
	v_mul_u32_u24_e32 v0, 0x900, v51
	v_or_b32_e32 v36, s6, v49
	v_mov_b32_e32 v37, s7
	v_lshl_add_u64 v[36:37], v[0:1], 0, v[36:37]
	v_mad_u32_u24 v0, v60, s60, v50
	v_and_b32_e32 v34, 0xffffffc0, v46
	s_mov_b64 s[0:1], 0x100
	ds_write2_b32 v0, v18, v19 offset1:33
	ds_write2_b32 v0, v20, v21 offset0:66 offset1:99
	v_add_u32_e32 v18, 0x400, v0
	v_lshl_add_u64 v[36:37], v[36:37], 0, s[0:1]
	ds_write2_b32 v18, v22, v23 offset0:8 offset1:41
	ds_write2_b32 v18, v24, v25 offset0:74 offset1:107
	v_add_u32_e32 v18, 0x800, v0
	v_add_u32_e32 v0, 0xc00, v0
	v_ashrrev_i32_e32 v35, 31, v34
	v_readlane_b32 s0, v254, 12
	ds_write2_b32 v18, v26, v27 offset0:16 offset1:49
	ds_write2_b32 v18, v28, v29 offset0:82 offset1:115
	ds_write2_b32 v0, v30, v31 offset0:24 offset1:57
	ds_write2_b32 v0, v32, v33 offset0:90 offset1:123
	v_lshl_add_u64 v[26:27], v[36:37], 0, v[34:35]
	v_readlane_b32 s1, v254, 13
	s_waitcnt lgkmcnt(0)
	v_add_u32_e32 v0, v49, v34
	v_cmp_lt_i32_e32 vcc, 0, v0
	v_lshl_add_u64 v[28:29], v[26:27], 1, s[0:1]
	global_load_dwordx4 v[18:21], v[28:29], off offset:16
	global_load_dwordx4 v[22:25], v[28:29], off
	v_mov_b32_e32 v32, 0
	v_mov_b32_e32 v41, 0
	s_and_saveexec_b64 s[0:1], vcc
	s_cbranch_execz .LBB0_896
	global_load_ushort v30, v[28:29], off offset:-2
	s_waitcnt vmcnt(0)
	v_lshlrev_b32_e32 v41, 16, v30
